# batched epilogues (residual GEMMs, branch merge, mLSTM read-modify-write) + software-pipelined LDS fragment reads in the gemm_in K-loop
# speedup vs baseline: 1.0412x; 1.0412x over previous
.LBB0_267:
	s_add_i32 s4, s1, 2
	s_cmp_lt_u32 s1, 14
	s_cselect_b64 s[6:7], -1, 0
	s_and_b64 vcc, s[6:7], exec
	s_cselect_b32 s2, s0, 0x3c0
	s_lshl_b64 s[6:7], s[2:3], 1
	ds_read_b128 v[138:141], v134
	ds_read_b128 v[146:149], v135 offset:18432
	ds_read_b128 v[142:145], v134 offset:4608
	ds_read_b128 v[150:153], v135 offset:23040
	ds_read_b128 v[154:157], v134 offset:32
	ds_read_b128 v[162:165], v135 offset:18464
	ds_read_b128 v[158:161], v134 offset:4640
	ds_read_b128 v[166:169], v135 offset:23072
	v_lshl_add_u64 v[170:171], v[130:131], 0, s[6:7]
	v_lshl_add_u64 v[172:173], v[132:133], 0, s[6:7]
	global_load_dwordx4 v[98:101], v[170:171], off
	global_load_dwordx4 v[102:105], v[172:173], off
	v_lshl_add_u64 v[174:175], v[170:171], 0, s[40:41]
	global_load_dwordx4 v[106:109], v[174:175], off
	v_lshl_add_u64 v[174:175], v[172:173], 0, s[40:41]
	global_load_dwordx4 v[110:113], v[174:175], off
	v_lshl_add_u64 v[174:175], v[170:171], 0, s[18:19]
	global_load_dwordx4 v[114:117], v[174:175], off
	v_lshl_add_u64 v[174:175], v[172:173], 0, s[18:19]
	global_load_dwordx4 v[118:121], v[174:175], off
	v_lshl_add_u64 v[174:175], v[170:171], 0, s[92:93]
	global_load_dwordx4 v[122:125], v[174:175], off
	v_lshl_add_u64 v[174:175], v[172:173], 0, s[92:93]
	global_load_dwordx4 v[126:129], v[174:175], off
	s_waitcnt lgkmcnt(4)
	v_mfma_f32_32x32x16_bf16 v[48:63], v[138:141], v[146:149], v[48:63]
	v_mfma_f32_32x32x16_bf16 v[32:47], v[138:141], v[150:153], v[32:47]
	v_mfma_f32_32x32x16_bf16 v[16:31], v[142:145], v[146:149], v[16:31]
	v_mfma_f32_32x32x16_bf16 v[0:15], v[142:145], v[150:153], v[0:15]
	ds_read_b128 v[138:141], v134 offset:64
	ds_read_b128 v[146:149], v135 offset:18496
	ds_read_b128 v[142:145], v134 offset:4672
	ds_read_b128 v[150:153], v135 offset:23104
	s_waitcnt lgkmcnt(4)
	v_mfma_f32_32x32x16_bf16 v[48:63], v[154:157], v[162:165], v[48:63]
	v_mfma_f32_32x32x16_bf16 v[32:47], v[154:157], v[166:169], v[32:47]
	v_mfma_f32_32x32x16_bf16 v[16:31], v[158:161], v[162:165], v[16:31]
	v_mfma_f32_32x32x16_bf16 v[0:15], v[158:161], v[166:169], v[0:15]
	ds_read_b128 v[154:157], v134 offset:96
	ds_read_b128 v[162:165], v135 offset:18528
	ds_read_b128 v[158:161], v134 offset:4704
	ds_read_b128 v[166:169], v135 offset:23136
	s_waitcnt lgkmcnt(4)
	v_mfma_f32_32x32x16_bf16 v[48:63], v[138:141], v[146:149], v[48:63]
	s_waitcnt vmcnt(8)
	ds_write_b128 v97, v[64:67] offset:36864
	ds_write_b128 v97, v[68:71] offset:55296
	v_mfma_f32_32x32x16_bf16 v[32:47], v[138:141], v[150:153], v[32:47]
	ds_write_b128 v97, v[72:75] offset:41472
	ds_write_b128 v97, v[76:79] offset:59904
	v_mfma_f32_32x32x16_bf16 v[16:31], v[142:145], v[146:149], v[16:31]
	ds_write_b128 v97, v[80:83] offset:46080
	ds_write_b128 v97, v[84:87] offset:64512
	v_mfma_f32_32x32x16_bf16 v[0:15], v[142:145], v[150:153], v[0:15]
	ds_write_b128 v97, v[88:91] offset:50688
	ds_write_b128 v136, v[92:95] offset:55296
	s_waitcnt lgkmcnt(8)
	v_mfma_f32_32x32x16_bf16 v[48:63], v[154:157], v[162:165], v[48:63]
	v_mfma_f32_32x32x16_bf16 v[32:47], v[154:157], v[166:169], v[32:47]
	v_mfma_f32_32x32x16_bf16 v[16:31], v[158:161], v[162:165], v[16:31]
	v_mfma_f32_32x32x16_bf16 v[0:15], v[158:161], v[166:169], v[0:15]
	s_waitcnt lgkmcnt(0)
	s_barrier
	s_min_u32 s1, s1, 12
	s_lshl_b32 s2, s1, 7
	s_addk_i32 s0, 0x80
	s_mov_b32 s1, s4
	ds_read_b128 v[138:141], v134 offset:36864
	ds_read_b128 v[146:149], v135 offset:55296
	ds_read_b128 v[142:145], v134 offset:41472
	ds_read_b128 v[150:153], v135 offset:59904
	ds_read_b128 v[154:157], v134 offset:36896
	ds_read_b128 v[162:165], v135 offset:55328
	ds_read_b128 v[158:161], v134 offset:41504
	ds_read_b128 v[166:169], v135 offset:59936
	v_lshl_add_u64 v[170:171], v[130:131], 0, s[2:3]
	v_lshl_add_u64 v[172:173], v[132:133], 0, s[2:3]
	v_lshl_add_u64 v[174:175], v[170:171], 0, s[22:23]
	global_load_dwordx4 v[64:67], v[174:175], off
	v_lshl_add_u64 v[174:175], v[172:173], 0, s[22:23]
	global_load_dwordx4 v[68:71], v[174:175], off
	v_lshl_add_u64 v[174:175], v[170:171], 0, s[76:77]
	global_load_dwordx4 v[72:75], v[174:175], off
	v_lshl_add_u64 v[174:175], v[172:173], 0, s[76:77]
	global_load_dwordx4 v[76:79], v[174:175], off
	v_lshl_add_u64 v[174:175], v[170:171], 0, s[26:27]
	global_load_dwordx4 v[80:83], v[174:175], off
	v_lshl_add_u64 v[174:175], v[172:173], 0, s[26:27]
	global_load_dwordx4 v[84:87], v[174:175], off
	v_lshl_add_u64 v[174:175], v[170:171], 0, s[70:71]
	global_load_dwordx4 v[88:91], v[174:175], off
	v_lshl_add_u64 v[174:175], v[172:173], 0, s[70:71]
	global_load_dwordx4 v[92:95], v[174:175], off
	s_waitcnt lgkmcnt(4)
	v_mfma_f32_32x32x16_bf16 v[48:63], v[138:141], v[146:149], v[48:63]
	v_mfma_f32_32x32x16_bf16 v[32:47], v[138:141], v[150:153], v[32:47]
	v_mfma_f32_32x32x16_bf16 v[16:31], v[142:145], v[146:149], v[16:31]
	v_mfma_f32_32x32x16_bf16 v[0:15], v[142:145], v[150:153], v[0:15]
	ds_read_b128 v[138:141], v134 offset:36928
	ds_read_b128 v[146:149], v135 offset:55360
	ds_read_b128 v[142:145], v134 offset:41536
	ds_read_b128 v[150:153], v135 offset:59968
	s_waitcnt lgkmcnt(4)
	v_mfma_f32_32x32x16_bf16 v[48:63], v[154:157], v[162:165], v[48:63]
	v_mfma_f32_32x32x16_bf16 v[32:47], v[154:157], v[166:169], v[32:47]
	v_mfma_f32_32x32x16_bf16 v[16:31], v[158:161], v[162:165], v[16:31]
	v_mfma_f32_32x32x16_bf16 v[0:15], v[158:161], v[166:169], v[0:15]
	ds_read_b128 v[154:157], v134 offset:36960
	ds_read_b128 v[162:165], v135 offset:55392
	ds_read_b128 v[158:161], v134 offset:41568
	ds_read_b128 v[166:169], v135 offset:60000
	s_waitcnt lgkmcnt(4)
	v_mfma_f32_32x32x16_bf16 v[48:63], v[138:141], v[146:149], v[48:63]
	s_waitcnt vmcnt(8)
	ds_write_b128 v97, v[98:101]
	ds_write_b128 v97, v[102:105] offset:18432
	v_mfma_f32_32x32x16_bf16 v[32:47], v[138:141], v[150:153], v[32:47]
	ds_write_b128 v97, v[106:109] offset:4608
	ds_write_b128 v97, v[110:113] offset:23040
	v_mfma_f32_32x32x16_bf16 v[16:31], v[142:145], v[146:149], v[16:31]
	ds_write_b128 v97, v[114:117] offset:9216
	ds_write_b128 v97, v[118:121] offset:27648
	v_mfma_f32_32x32x16_bf16 v[0:15], v[142:145], v[150:153], v[0:15]
	ds_write_b128 v97, v[122:125] offset:13824
	ds_write_b128 v97, v[126:129] offset:32256
	s_waitcnt lgkmcnt(8)
	v_mfma_f32_32x32x16_bf16 v[48:63], v[154:157], v[162:165], v[48:63]
	v_mfma_f32_32x32x16_bf16 v[32:47], v[154:157], v[166:169], v[32:47]
	v_mfma_f32_32x32x16_bf16 v[16:31], v[158:161], v[162:165], v[16:31]
	v_mfma_f32_32x32x16_bf16 v[0:15], v[158:161], v[166:169], v[0:15]
	s_waitcnt lgkmcnt(0)
	s_barrier
	s_cbranch_vccnz .LBB0_267
	s_cmp_gt_i32 s59, 7
	s_cselect_b64 s[50:51], -1, 0
	s_cmp_lt_i32 s59, 8
	s_cselect_b64 s[0:1], -1, 0
	s_sub_i32 s2, s59, 32
	s_cmp_lt_u32 s2, 40
	s_waitcnt vmcnt(0)
	s_cselect_b64 s[4:5], -1, 0
	s_or_b64 s[0:1], s[0:1], s[4:5]
	v_mov_b32_e32 v64, v244
	s_andn2_b64 vcc, exec, s[0:1]
	s_mov_b64 s[0:1], -1
	s_cbranch_vccz .LBB0_383
	v_ashrrev_i32_e32 v107, 7, v64
	v_bfe_u32 v108, v64, 6, 1
	v_and_b32_e32 v106, 31, v64
	v_bfe_u32 v97, v64, 5, 1
	s_cmp_gt_u32 s59, 15
	s_cbranch_scc0 .LBB0_373
	s_cmp_gt_u32 s59, 31
	s_cbranch_scc0 .LBB0_338
	v_cmp_eq_u32_e32 vcc, 0, v108
	v_cmp_gt_u32_e64 s[0:1], 16, v106
	s_and_b64 s[0:1], vcc, s[0:1]
	s_and_saveexec_b64 s[4:5], s[0:1]
	s_cbranch_execz .LBB0_337
	v_or_b32_e32 v66, s58, v106
	v_mov_b32_e32 v67, v96
	v_lshl_add_u64 v[66:67], v[66:67], 2, s[8:9]
	global_load_dword v68, v[66:67], off
	v_and_b32_e32 v64, 4, v64
	v_cmp_ne_u32_e32 vcc, 0, v64
	s_waitcnt vmcnt(0)
	v_add_f32_e32 v69, v48, v68
	s_and_saveexec_b64 s[6:7], vcc
	s_cbranch_execz .LBB0_274
	v_mul_f32_e64 v64, |v69|, s69
	v_exp_f32_e32 v80, v64
	v_max_f32_e32 v64, v69, v69
	v_min_f32_e32 v69, 0, v64
	s_mov_b32 s0, 0x3f2aaaab
	v_add_f32_e32 v66, 1.0, v80
	v_add_f32_e32 v64, -1.0, v66
	v_sub_f32_e32 v65, v64, v66
	v_sub_f32_e32 v64, v80, v64
	v_add_f32_e32 v65, 1.0, v65
	v_add_f32_e32 v67, v64, v65
	v_frexp_mant_f32_e32 v70, v66
	v_cvt_f64_f32_e32 v[64:65], v66
	v_frexp_exp_i32_f64_e32 v64, v[64:65]
	v_cmp_gt_f32_e64 s[0:1], s0, v70
	s_nop 1
	v_subbrev_co_u32_e64 v74, s[0:1], 0, v64, s[0:1]
	v_sub_u32_e32 v64, 0, v74
	v_ldexp_f32 v65, v66, v64
	v_add_f32_e32 v66, -1.0, v65
	v_add_f32_e32 v70, 1.0, v65
	v_ldexp_f32 v64, v67, v64
	v_add_f32_e32 v67, 1.0, v66
	v_add_f32_e32 v71, -1.0, v70
	v_sub_f32_e32 v67, v65, v67
	v_sub_f32_e32 v65, v65, v71
	v_add_f32_e32 v67, v64, v67
	v_add_f32_e32 v64, v64, v65
	v_add_f32_e32 v75, v70, v64
	v_rcp_f32_e32 v77, v75
	v_sub_f32_e32 v65, v75, v70
	v_sub_f32_e32 v76, v64, v65
	v_add_f32_e32 v65, v66, v67
	v_mul_f32_e32 v79, v65, v77
	v_sub_f32_e32 v64, v65, v66
	v_mul_f32_e32 v66, v75, v79
	v_fma_f32 v70, v79, v75, -v66
	v_fmac_f32_e32 v70, v79, v76
	v_sub_f32_e32 v78, v67, v64
	v_add_f32_e32 v64, v66, v70
	v_sub_f32_e32 v67, v65, v64
	v_pk_add_f32 v[72:73], v[64:65], v[66:67] neg_lo:[0,1] neg_hi:[0,1]
	v_mov_b32_e32 v71, v64
	v_pk_add_f32 v[64:65], v[72:73], v[70:71] neg_lo:[0,1] neg_hi:[0,1]
	s_mov_b32 s0, 0x3f317218
	v_add_f32_e32 v65, v78, v65
	v_add_f32_e32 v64, v64, v65
	v_add_f32_e32 v65, v67, v64
	v_mul_f32_e32 v78, v77, v65
	v_mul_f32_e32 v66, v75, v78
	v_fma_f32 v70, v78, v75, -v66
	v_fmac_f32_e32 v70, v78, v76
	v_sub_f32_e32 v67, v67, v65
	v_add_f32_e32 v75, v64, v67
	v_add_f32_e32 v64, v66, v70
	v_sub_f32_e32 v67, v65, v64
	v_pk_add_f32 v[72:73], v[64:65], v[66:67] neg_lo:[0,1] neg_hi:[0,1]
	v_mov_b32_e32 v71, v64
	v_pk_add_f32 v[64:65], v[72:73], v[70:71] neg_lo:[0,1] neg_hi:[0,1]
	s_nop 0
	v_add_f32_e32 v65, v75, v65
	v_add_f32_e32 v64, v64, v65
	v_add_f32_e32 v65, v79, v78
	v_add_f32_e32 v64, v67, v64
	v_sub_f32_e32 v66, v65, v79
	v_mul_f32_e32 v64, v77, v64
	v_sub_f32_e32 v66, v78, v66
	v_add_f32_e32 v66, v66, v64
	v_add_f32_e32 v70, v65, v66
	v_mul_f32_e32 v71, v70, v70
	v_fmamk_f32 v64, v71, 0x3e9b6dac, v253
	v_fmaak_f32 v179, v71, v64, 0x3f2aaada
	v_cvt_f32_i32_e32 v64, v74
	v_sub_f32_e32 v65, v70, v65
	v_sub_f32_e32 v65, v66, v65
	v_ldexp_f32 v72, v65, 1
	v_mul_f32_e32 v65, v70, v71
	v_ldexp_f32 v67, v70, 1
	v_pk_mul_f32 v[70:71], v[64:65], v[178:179]
	s_nop 0
	v_fma_f32 v66, v64, s0, -v70
	v_fmac_f32_e32 v66, 0xb102e308, v64
	v_pk_add_f32 v[64:65], v[70:71], v[66:67]
	s_mov_b32 s0, 0x7f800000
	v_sub_f32_e32 v67, v65, v67
	v_sub_f32_e32 v67, v71, v67
	v_add_f32_e32 v73, v72, v67
	v_mov_b32_e32 v72, v70
	v_pk_add_f32 v[70:71], v[64:65], v[70:71] neg_lo:[0,1] neg_hi:[0,1]
	v_pk_add_f32 v[74:75], v[64:65], v[72:73]
	v_mov_b32_e32 v67, v64
	v_mov_b32_e32 v71, v75
	v_pk_add_f32 v[76:77], v[66:67], v[70:71] neg_lo:[0,1] neg_hi:[0,1]
	v_pk_add_f32 v[66:67], v[66:67], v[70:71]
	v_mov_b32_e32 v72, v73
	v_pk_add_f32 v[70:71], v[66:67], v[64:65] op_sel:[1,0] op_sel_hi:[0,1] neg_lo:[0,1] neg_hi:[0,1]
	v_pk_add_f32 v[78:79], v[74:75], v[70:71] op_sel_hi:[1,0] neg_lo:[0,1] neg_hi:[0,1]
	v_mov_b32_e32 v74, v75
	v_mov_b32_e32 v75, v67
	v_pk_mov_b32 v[70:71], v[64:65], v[70:71] op_sel:[1,0]
	v_mov_b32_e32 v73, v64
	v_pk_add_f32 v[70:71], v[74:75], v[70:71] neg_lo:[0,1] neg_hi:[0,1]
	v_mov_b32_e32 v78, v76
	v_pk_add_f32 v[64:65], v[72:73], v[70:71] neg_lo:[0,1] neg_hi:[0,1]
	v_mov_b32_e32 v77, v67
	v_pk_add_f32 v[70:71], v[78:79], v[64:65]
	v_cmp_neq_f32_e64 s[0:1], s0, v80
	v_pk_add_f32 v[72:73], v[70:71], v[70:71] op_sel:[0,1] op_sel_hi:[1,0]
	s_nop 0
	v_pk_add_f32 v[66:67], v[66:67], v[72:73] op_sel:[1,0] op_sel_hi:[0,1]
	v_mov_b32_e32 v71, v66
	v_pk_add_f32 v[74:75], v[70:71], v[76:77] neg_lo:[0,1] neg_hi:[0,1]
	v_mov_b32_e32 v65, v72
	v_sub_f32_e32 v67, v70, v74
	v_pk_add_f32 v[64:65], v[64:65], v[74:75] neg_lo:[0,1] neg_hi:[0,1]
	v_sub_f32_e32 v67, v76, v67
	v_add_f32_e32 v64, v64, v67
	v_add_f32_e32 v64, v64, v65
	v_add_f32_e32 v64, v66, v64
	v_cndmask_b32_e64 v64, v243, v64, s[0:1]
	v_cmp_ngt_f32_e64 s[0:1], -1.0, v80
	s_nop 1
	v_cndmask_b32_e64 v64, v245, v64, s[0:1]
	v_cmp_neq_f32_e64 s[0:1], -1.0, v80
	s_nop 1
	v_cndmask_b32_e64 v64, v246, v64, s[0:1]
	s_mov_b32 s0, 0x33800000
	v_cmp_lt_f32_e64 s[0:1], |v80|, s0
	s_nop 1
	v_cndmask_b32_e64 v64, v64, v80, s[0:1]
	v_sub_f32_e32 v69, v69, v64

.LBB0_635:
	v_and_b32_e32 v98, 64, v251
	v_xor_b32_e32 v97, 16, v251
	v_add_u32_e32 v99, 64, v98
	v_cmp_lt_i32_e32 vcc, v97, v99
	v_xor_b32_e32 v100, 32, v251
	s_xor_b64 s[38:39], s[4:5], -1
	v_cndmask_b32_e32 v97, v251, v97, vcc
	v_lshlrev_b32_e32 v97, 2, v97
	ds_bpermute_b32 v97, v97, v226
	v_cmp_lt_i32_e32 vcc, v100, v99
	v_or_b32_e32 v98, v98, v185
	v_lshlrev_b32_e32 v98, 2, v98
	v_cndmask_b32_e32 v99, v251, v100, vcc
	s_waitcnt lgkmcnt(0)
	v_add_f32_e32 v97, v226, v97
	v_lshlrev_b32_e32 v99, 2, v99
	ds_bpermute_b32 v99, v99, v97
	v_max_f32_e32 v100, v223, v223
	v_mov_b64_e32 v[104:105], v[170:171]
	s_waitcnt lgkmcnt(0)
	v_add_f32_e32 v97, v97, v99
	v_max_f32_e64 v97, |v97|, v100
	v_div_scale_f32 v99, s[4:5], v97, v97, 1.0
	v_rcp_f32_e32 v100, v99
	v_div_scale_f32 v101, vcc, 1.0, v97, 1.0
	s_mov_b64 s[4:5], -1
	v_fma_f32 v102, -v99, v100, 1.0
	v_fmac_f32_e32 v100, v102, v100
	v_mul_f32_e32 v102, v101, v100
	v_fma_f32 v103, -v99, v102, v101
	v_fmac_f32_e32 v102, v103, v100
	v_fma_f32 v99, -v99, v102, v101
	v_div_fmas_f32 v99, v99, v100, v102
	v_div_fixup_f32 v97, v99, v97, 1.0
	ds_bpermute_b32 v108, v98, v97
	ds_bpermute_b32 v107, v98, v97 offset:4
	ds_bpermute_b32 v106, v98, v97 offset:8
	v_or_b32_e32 v98, 12, v98
	ds_bpermute_b32 v97, v98, v97
	v_lshl_add_u64 v[102:103], v[104:105], 0, s[28:29]
	v_lshl_add_u64 v[100:101], v[104:105], 0, s[24:25]
	v_lshl_add_u64 v[98:99], v[104:105], 0, s[30:31]
	s_waitcnt lgkmcnt(3)
	v_mul_f32_e32 v92, v92, v108
	s_and_b64 vcc, exec, s[38:39]
	s_cbranch_vccz .LBB0_637
	s_waitcnt lgkmcnt(0)
	global_load_ushort v110, v[104:105], off
	global_load_ushort v111, v[102:103], off
	global_load_ushort v112, v[100:101], off
	global_load_ushort v113, v[98:99], off
	global_load_ushort v114, v[104:105], off offset:32
	global_load_ushort v115, v[102:103], off offset:32
	global_load_ushort v116, v[100:101], off offset:32
	global_load_ushort v117, v[98:99], off offset:32
	global_load_ushort v118, v[104:105], off offset:64
	global_load_ushort v119, v[102:103], off offset:64
	global_load_ushort v120, v[100:101], off offset:64
	global_load_ushort v121, v[98:99], off offset:64
	global_load_ushort v122, v[104:105], off offset:96
	global_load_ushort v123, v[102:103], off offset:96
	global_load_ushort v124, v[100:101], off offset:96
	global_load_ushort v125, v[98:99], off offset:96
	global_load_ushort v126, v[104:105], off offset:128
	global_load_ushort v127, v[102:103], off offset:128
	global_load_ushort v128, v[100:101], off offset:128
	global_load_ushort v129, v[98:99], off offset:128
	global_load_ushort v130, v[104:105], off offset:160
	global_load_ushort v131, v[102:103], off offset:160
	global_load_ushort v132, v[100:101], off offset:160
	global_load_ushort v133, v[98:99], off offset:160
	global_load_ushort v134, v[104:105], off offset:192
	global_load_ushort v135, v[102:103], off offset:192
	global_load_ushort v136, v[100:101], off offset:192
	global_load_ushort v137, v[98:99], off offset:192
	global_load_ushort v138, v[104:105], off offset:224
	global_load_ushort v139, v[102:103], off offset:224
	global_load_ushort v140, v[100:101], off offset:224
	global_load_ushort v141, v[98:99], off offset:224
	s_waitcnt vmcnt(0)
	v_lshlrev_b32_e32 v110, 16, v110
	v_add_f32_e32 v110, v92, v110
	v_cvt_pk_bf16_f32 v110, v110, v110
	v_lshlrev_b32_e32 v111, 16, v111
	v_fmac_f32_e32 v111, v93, v107
	v_cvt_pk_bf16_f32 v111, v111, v111
	v_lshlrev_b32_e32 v112, 16, v112
	v_fmac_f32_e32 v112, v94, v106
	v_cvt_pk_bf16_f32 v112, v112, v112
	v_lshlrev_b32_e32 v113, 16, v113
	v_fmac_f32_e32 v113, v95, v97
	v_cvt_pk_bf16_f32 v113, v113, v113
	v_lshlrev_b32_e32 v114, 16, v114
	v_fmac_f32_e32 v114, v88, v108
	v_cvt_pk_bf16_f32 v114, v114, v114
	v_lshlrev_b32_e32 v115, 16, v115
	v_fmac_f32_e32 v115, v89, v107
	v_cvt_pk_bf16_f32 v115, v115, v115
	v_lshlrev_b32_e32 v116, 16, v116
	v_fmac_f32_e32 v116, v90, v106
	v_cvt_pk_bf16_f32 v116, v116, v116
	v_lshlrev_b32_e32 v117, 16, v117
	v_fmac_f32_e32 v117, v91, v97
	v_cvt_pk_bf16_f32 v117, v117, v117
	v_lshlrev_b32_e32 v118, 16, v118
	v_fmac_f32_e32 v118, v84, v108
	v_cvt_pk_bf16_f32 v118, v118, v118
	v_lshlrev_b32_e32 v119, 16, v119
	v_fmac_f32_e32 v119, v85, v107
	v_cvt_pk_bf16_f32 v119, v119, v119
	v_lshlrev_b32_e32 v120, 16, v120
	v_fmac_f32_e32 v120, v86, v106
	v_cvt_pk_bf16_f32 v120, v120, v120
	v_lshlrev_b32_e32 v121, 16, v121
	v_fmac_f32_e32 v121, v87, v97
	v_cvt_pk_bf16_f32 v121, v121, v121
	v_lshlrev_b32_e32 v122, 16, v122
	v_fmac_f32_e32 v122, v80, v108
	v_cvt_pk_bf16_f32 v122, v122, v122
	v_lshlrev_b32_e32 v123, 16, v123
	v_fmac_f32_e32 v123, v81, v107
	v_cvt_pk_bf16_f32 v123, v123, v123
	v_lshlrev_b32_e32 v124, 16, v124
	v_fmac_f32_e32 v124, v82, v106
	v_cvt_pk_bf16_f32 v124, v124, v124
	v_lshlrev_b32_e32 v125, 16, v125
	v_fmac_f32_e32 v125, v83, v97
	v_cvt_pk_bf16_f32 v125, v125, v125
	v_lshlrev_b32_e32 v126, 16, v126
	v_fmac_f32_e32 v126, v76, v108
	v_cvt_pk_bf16_f32 v126, v126, v126
	v_lshlrev_b32_e32 v127, 16, v127
	v_fmac_f32_e32 v127, v77, v107
	v_cvt_pk_bf16_f32 v127, v127, v127
	v_lshlrev_b32_e32 v128, 16, v128
	v_fmac_f32_e32 v128, v78, v106
	v_cvt_pk_bf16_f32 v128, v128, v128
	v_lshlrev_b32_e32 v129, 16, v129
	v_fmac_f32_e32 v129, v79, v97
	v_cvt_pk_bf16_f32 v129, v129, v129
	v_lshlrev_b32_e32 v130, 16, v130
	v_fmac_f32_e32 v130, v72, v108
	v_cvt_pk_bf16_f32 v130, v130, v130
	v_lshlrev_b32_e32 v131, 16, v131
	v_fmac_f32_e32 v131, v73, v107
	v_cvt_pk_bf16_f32 v131, v131, v131
	v_lshlrev_b32_e32 v132, 16, v132
	v_fmac_f32_e32 v132, v74, v106
	v_cvt_pk_bf16_f32 v132, v132, v132
	v_lshlrev_b32_e32 v133, 16, v133
	v_fmac_f32_e32 v133, v75, v97
	v_cvt_pk_bf16_f32 v133, v133, v133
	v_lshlrev_b32_e32 v134, 16, v134
	v_fmac_f32_e32 v134, v64, v108
	v_cvt_pk_bf16_f32 v134, v134, v134
	v_lshlrev_b32_e32 v135, 16, v135
	v_fmac_f32_e32 v135, v65, v107
	v_cvt_pk_bf16_f32 v135, v135, v135
	v_lshlrev_b32_e32 v136, 16, v136
	v_fmac_f32_e32 v136, v66, v106
	v_cvt_pk_bf16_f32 v136, v136, v136
	v_lshlrev_b32_e32 v137, 16, v137
	v_fmac_f32_e32 v137, v67, v97
	v_cvt_pk_bf16_f32 v137, v137, v137
	v_lshlrev_b32_e32 v138, 16, v138
	v_fmac_f32_e32 v138, v52, v108
	v_cvt_pk_bf16_f32 v138, v138, v138
	v_lshlrev_b32_e32 v139, 16, v139
	v_fmac_f32_e32 v139, v53, v107
	v_cvt_pk_bf16_f32 v139, v139, v139
	v_lshlrev_b32_e32 v140, 16, v140
	v_fmac_f32_e32 v140, v54, v106
	v_cvt_pk_bf16_f32 v140, v140, v140
	v_lshlrev_b32_e32 v141, 16, v141
	v_fmac_f32_e32 v141, v55, v97
	v_cvt_pk_bf16_f32 v141, v141, v141
	global_store_short v[104:105], v110, off
	global_store_short v[102:103], v111, off
	global_store_short v[100:101], v112, off
	global_store_short v[98:99], v113, off
	global_store_short v[104:105], v114, off offset:32
	global_store_short v[102:103], v115, off offset:32
	global_store_short v[100:101], v116, off offset:32
	global_store_short v[98:99], v117, off offset:32
	global_store_short v[104:105], v118, off offset:64
	global_store_short v[102:103], v119, off offset:64
	global_store_short v[100:101], v120, off offset:64
	global_store_short v[98:99], v121, off offset:64
	global_store_short v[104:105], v122, off offset:96
	global_store_short v[102:103], v123, off offset:96
	global_store_short v[100:101], v124, off offset:96
	global_store_short v[98:99], v125, off offset:96
	global_store_short v[104:105], v126, off offset:128
	global_store_short v[102:103], v127, off offset:128
	global_store_short v[100:101], v128, off offset:128
	global_store_short v[98:99], v129, off offset:128
	global_store_short v[104:105], v130, off offset:160
	global_store_short v[102:103], v131, off offset:160
	global_store_short v[100:101], v132, off offset:160
	global_store_short v[98:99], v133, off offset:160
	global_store_short v[104:105], v134, off offset:192
	global_store_short v[102:103], v135, off offset:192
	global_store_short v[100:101], v136, off offset:192
	global_store_short v[98:99], v137, off offset:192
	global_store_short v[104:105], v138, off offset:224
	global_store_short v[102:103], v139, off offset:224
	global_store_short v[100:101], v140, off offset:224
	global_store_short v[98:99], v141, off offset:224
	global_load_ushort v110, v[104:105], off offset:256
	global_load_ushort v111, v[102:103], off offset:256
	global_load_ushort v112, v[100:101], off offset:256
	global_load_ushort v113, v[98:99], off offset:256
	global_load_ushort v114, v[104:105], off offset:288
	global_load_ushort v115, v[102:103], off offset:288
	global_load_ushort v116, v[100:101], off offset:288
	global_load_ushort v117, v[98:99], off offset:288
	global_load_ushort v118, v[104:105], off offset:320
	global_load_ushort v119, v[102:103], off offset:320
	global_load_ushort v120, v[100:101], off offset:320
	global_load_ushort v121, v[98:99], off offset:320
	global_load_ushort v122, v[104:105], off offset:352
	global_load_ushort v123, v[102:103], off offset:352
	global_load_ushort v124, v[100:101], off offset:352
	global_load_ushort v125, v[98:99], off offset:352
	global_load_ushort v126, v[104:105], off offset:384
	global_load_ushort v127, v[102:103], off offset:384
	global_load_ushort v128, v[100:101], off offset:384
	global_load_ushort v129, v[98:99], off offset:384
	global_load_ushort v130, v[104:105], off offset:416
	global_load_ushort v131, v[102:103], off offset:416
	global_load_ushort v132, v[100:101], off offset:416
	global_load_ushort v133, v[98:99], off offset:416
	global_load_ushort v134, v[104:105], off offset:448
	global_load_ushort v135, v[102:103], off offset:448
	global_load_ushort v136, v[100:101], off offset:448
	global_load_ushort v137, v[98:99], off offset:448
	global_load_ushort v138, v[104:105], off offset:480
	global_load_ushort v139, v[102:103], off offset:480
	global_load_ushort v140, v[100:101], off offset:480
	global_load_ushort v141, v[98:99], off offset:480
	s_waitcnt vmcnt(0)
	v_lshlrev_b32_e32 v110, 16, v110
	v_fmac_f32_e32 v110, v68, v108
	v_cvt_pk_bf16_f32 v110, v110, v110
	v_lshlrev_b32_e32 v111, 16, v111
	v_fmac_f32_e32 v111, v69, v107
	v_cvt_pk_bf16_f32 v111, v111, v111
	v_lshlrev_b32_e32 v112, 16, v112
	v_fmac_f32_e32 v112, v70, v106
	v_cvt_pk_bf16_f32 v112, v112, v112
	v_lshlrev_b32_e32 v113, 16, v113
	v_fmac_f32_e32 v113, v71, v97
	v_cvt_pk_bf16_f32 v113, v113, v113
	v_lshlrev_b32_e32 v114, 16, v114
	v_fmac_f32_e32 v114, v60, v108
	v_cvt_pk_bf16_f32 v114, v114, v114
	v_lshlrev_b32_e32 v115, 16, v115
	v_fmac_f32_e32 v115, v61, v107
	v_cvt_pk_bf16_f32 v115, v115, v115
	v_lshlrev_b32_e32 v116, 16, v116
	v_fmac_f32_e32 v116, v62, v106
	v_cvt_pk_bf16_f32 v116, v116, v116
	v_lshlrev_b32_e32 v117, 16, v117
	v_fmac_f32_e32 v117, v63, v97
	v_cvt_pk_bf16_f32 v117, v117, v117
	v_lshlrev_b32_e32 v118, 16, v118
	v_fmac_f32_e32 v118, v56, v108
	v_cvt_pk_bf16_f32 v118, v118, v118
	v_lshlrev_b32_e32 v119, 16, v119
	v_fmac_f32_e32 v119, v57, v107
	v_cvt_pk_bf16_f32 v119, v119, v119
	v_lshlrev_b32_e32 v120, 16, v120
	v_fmac_f32_e32 v120, v58, v106
	v_cvt_pk_bf16_f32 v120, v120, v120
	v_lshlrev_b32_e32 v121, 16, v121
	v_fmac_f32_e32 v121, v59, v97
	v_cvt_pk_bf16_f32 v121, v121, v121
	v_lshlrev_b32_e32 v122, 16, v122
	v_fmac_f32_e32 v122, v48, v108
	v_cvt_pk_bf16_f32 v122, v122, v122
	v_lshlrev_b32_e32 v123, 16, v123
	v_fmac_f32_e32 v123, v49, v107
	v_cvt_pk_bf16_f32 v123, v123, v123
	v_lshlrev_b32_e32 v124, 16, v124
	v_fmac_f32_e32 v124, v50, v106
	v_cvt_pk_bf16_f32 v124, v124, v124
	v_lshlrev_b32_e32 v125, 16, v125
	v_fmac_f32_e32 v125, v51, v97
	v_cvt_pk_bf16_f32 v125, v125, v125
	v_lshlrev_b32_e32 v126, 16, v126
	v_fmac_f32_e32 v126, v44, v108
	v_cvt_pk_bf16_f32 v126, v126, v126
	v_lshlrev_b32_e32 v127, 16, v127
	v_fmac_f32_e32 v127, v45, v107
	v_cvt_pk_bf16_f32 v127, v127, v127
	v_lshlrev_b32_e32 v128, 16, v128
	v_fmac_f32_e32 v128, v46, v106
	v_cvt_pk_bf16_f32 v128, v128, v128
	v_lshlrev_b32_e32 v129, 16, v129
	v_fmac_f32_e32 v129, v47, v97
	v_cvt_pk_bf16_f32 v129, v129, v129
	v_lshlrev_b32_e32 v130, 16, v130
	v_fmac_f32_e32 v130, v40, v108
	v_cvt_pk_bf16_f32 v130, v130, v130
	v_lshlrev_b32_e32 v131, 16, v131
	v_fmac_f32_e32 v131, v41, v107
	v_cvt_pk_bf16_f32 v131, v131, v131
	v_lshlrev_b32_e32 v132, 16, v132
	v_fmac_f32_e32 v132, v42, v106
	v_cvt_pk_bf16_f32 v132, v132, v132
	v_lshlrev_b32_e32 v133, 16, v133
	v_fmac_f32_e32 v133, v43, v97
	v_cvt_pk_bf16_f32 v133, v133, v133
	v_lshlrev_b32_e32 v134, 16, v134
	v_fmac_f32_e32 v134, v36, v108
	v_cvt_pk_bf16_f32 v134, v134, v134
	v_lshlrev_b32_e32 v135, 16, v135
	v_fmac_f32_e32 v135, v37, v107
	v_cvt_pk_bf16_f32 v135, v135, v135
	v_lshlrev_b32_e32 v136, 16, v136
	v_fmac_f32_e32 v136, v38, v106
	v_cvt_pk_bf16_f32 v136, v136, v136
	v_lshlrev_b32_e32 v137, 16, v137
	v_fmac_f32_e32 v137, v39, v97
	v_cvt_pk_bf16_f32 v137, v137, v137
	v_lshlrev_b32_e32 v138, 16, v138
	v_fmac_f32_e32 v138, v32, v108
	v_cvt_pk_bf16_f32 v138, v138, v138
	v_lshlrev_b32_e32 v139, 16, v139
	v_fmac_f32_e32 v139, v33, v107
	v_cvt_pk_bf16_f32 v139, v139, v139
	v_lshlrev_b32_e32 v140, 16, v140
	v_fmac_f32_e32 v140, v34, v106
	v_cvt_pk_bf16_f32 v140, v140, v140
	v_lshlrev_b32_e32 v141, 16, v141
	v_fmac_f32_e32 v141, v35, v97
	v_cvt_pk_bf16_f32 v141, v141, v141
	global_store_short v[104:105], v110, off offset:256
	global_store_short v[102:103], v111, off offset:256
	global_store_short v[100:101], v112, off offset:256
	global_store_short v[98:99], v113, off offset:256
	global_store_short v[104:105], v114, off offset:288
	global_store_short v[102:103], v115, off offset:288
	global_store_short v[100:101], v116, off offset:288
	global_store_short v[98:99], v117, off offset:288
	global_store_short v[104:105], v118, off offset:320
	global_store_short v[102:103], v119, off offset:320
	global_store_short v[100:101], v120, off offset:320
	global_store_short v[98:99], v121, off offset:320
	global_store_short v[104:105], v122, off offset:352
	global_store_short v[102:103], v123, off offset:352
	global_store_short v[100:101], v124, off offset:352
	global_store_short v[98:99], v125, off offset:352
	global_store_short v[104:105], v126, off offset:384
	global_store_short v[102:103], v127, off offset:384
	global_store_short v[100:101], v128, off offset:384
	global_store_short v[98:99], v129, off offset:384
	global_store_short v[104:105], v130, off offset:416
	global_store_short v[102:103], v131, off offset:416
	global_store_short v[100:101], v132, off offset:416
	global_store_short v[98:99], v133, off offset:416
	global_store_short v[104:105], v134, off offset:448
	global_store_short v[102:103], v135, off offset:448
	global_store_short v[100:101], v136, off offset:448
	global_store_short v[98:99], v137, off offset:448
	global_store_short v[104:105], v138, off offset:480
	global_store_short v[102:103], v139, off offset:480
	global_store_short v[100:101], v140, off offset:480
	global_store_short v[98:99], v141, off offset:480
	s_cbranch_execnz .LBB0_622
	s_branch .LBB0_638

.LBB0_778:
	s_add_i32 s5, s6, 2
	s_cmp_lt_u32 s6, 30
	s_cselect_b64 s[10:11], -1, 0
	s_and_b64 vcc, s[10:11], exec
	s_cselect_b32 s2, s4, 0x7c0
	s_lshl_b64 s[10:11], s[2:3], 1
	v_lshl_add_u64 v[158:159], v[180:181], 0, s[10:11]
	global_load_dwordx4 v[138:141], v[158:159], off
	v_lshl_add_u64 v[146:147], v[158:159], 0, s[18:19]
	global_load_dwordx4 v[142:145], v[146:147], off
	v_lshl_add_u64 v[150:151], v[158:159], 0, s[62:63]
	global_load_dwordx4 v[146:149], v[150:151], off
	v_lshl_add_u64 v[154:155], v[158:159], 0, s[72:73]
	global_load_dwordx4 v[150:153], v[154:155], off
	v_lshl_add_u64 v[160:161], v[158:159], 0, s[52:53]
	global_load_dwordx4 v[154:157], v[160:161], off
	v_lshl_add_u64 v[162:163], v[158:159], 0, s[50:51]
	global_load_dwordx4 v[158:161], v[162:163], off
	v_lshl_add_u64 v[174:175], v[182:183], 0, s[10:11]
	global_load_dwordx4 v[162:165], v[174:175], off
	v_lshl_add_u64 v[170:171], v[174:175], 0, s[18:19]
	global_load_dwordx4 v[166:169], v[170:171], off
	v_lshl_add_u64 v[176:177], v[174:175], 0, s[62:63]
	global_load_dwordx4 v[170:173], v[176:177], off
	v_lshl_add_u64 v[186:187], v[174:175], 0, s[72:73]
	global_load_dwordx4 v[174:177], v[186:187], off
	ds_read_b128 v[186:189], v179 offset:4608
	ds_read_b128 v[190:193], v179 offset:9216
	ds_read_b128 v[194:197], v184 offset:32256
	ds_read_b128 v[198:201], v179
	ds_read_b128 v[202:205], v179 offset:32
	ds_read_b128 v[206:209], v184 offset:27648
	ds_read_b128 v[210:213], v184 offset:27680
	s_waitcnt lgkmcnt(0)
	v_mfma_f32_32x32x16_bf16 v[80:95], v[198:201], v[206:209], v[80:95]
	s_min_u32 s2, s6, 28
	s_lshl_b32 s2, s2, 7
	s_mov_b64 s[6:7], 0x80180
	s_addk_i32 s4, 0x80
	v_mfma_f32_32x32x16_bf16 v[64:79], v[198:201], v[194:197], v[64:79]
	v_mfma_f32_32x32x16_bf16 v[48:63], v[186:189], v[206:209], v[48:63]
	v_mfma_f32_32x32x16_bf16 v[32:47], v[186:189], v[194:197], v[32:47]
	v_mfma_f32_32x32x16_bf16 v[16:31], v[190:193], v[206:209], v[16:31]
	v_mfma_f32_32x32x16_bf16 v[0:15], v[190:193], v[194:197], v[0:15]
	ds_read_b128 v[186:189], v179 offset:4640
	ds_read_b128 v[190:193], v179 offset:9248
	ds_read_b128 v[194:197], v184 offset:32288
	v_mfma_f32_32x32x16_bf16 v[80:95], v[202:205], v[210:213], v[80:95]
	s_waitcnt lgkmcnt(0)
	v_mfma_f32_32x32x16_bf16 v[64:79], v[202:205], v[194:197], v[64:79]
	v_mfma_f32_32x32x16_bf16 v[48:63], v[186:189], v[210:213], v[48:63]
	v_mfma_f32_32x32x16_bf16 v[32:47], v[186:189], v[194:197], v[32:47]
	v_mfma_f32_32x32x16_bf16 v[16:31], v[190:193], v[210:213], v[16:31]
	v_mfma_f32_32x32x16_bf16 v[0:15], v[190:193], v[194:197], v[0:15]
	ds_read_b128 v[186:189], v179 offset:64
	ds_read_b128 v[190:193], v179 offset:4672
	ds_read_b128 v[194:197], v179 offset:9280
	ds_read_b128 v[198:201], v184 offset:27712
	ds_read_b128 v[202:205], v184 offset:32320
	s_waitcnt lgkmcnt(0)
	v_mfma_f32_32x32x16_bf16 v[80:95], v[186:189], v[198:201], v[80:95]
	v_mfma_f32_32x32x16_bf16 v[64:79], v[186:189], v[202:205], v[64:79]
	v_mfma_f32_32x32x16_bf16 v[48:63], v[190:193], v[198:201], v[48:63]
	v_mfma_f32_32x32x16_bf16 v[32:47], v[190:193], v[202:205], v[32:47]
	v_mfma_f32_32x32x16_bf16 v[16:31], v[194:197], v[198:201], v[16:31]
	v_mfma_f32_32x32x16_bf16 v[0:15], v[194:197], v[202:205], v[0:15]
	ds_read_b128 v[186:189], v179 offset:96
	ds_read_b128 v[190:193], v179 offset:4704
	ds_read_b128 v[194:197], v179 offset:9312
	ds_read_b128 v[198:201], v184 offset:27744
	ds_read_b128 v[202:205], v184 offset:32352
	s_waitcnt vmcnt(10)
	s_waitcnt lgkmcnt(0)
	s_barrier
	ds_write_b128 v97, v[98:101]
	ds_write_b128 v97, v[102:105] offset:4608
	ds_write_b128 v97, v[106:109] offset:9216
	ds_write_b128 v97, v[110:113] offset:13824
	ds_write_b128 v97, v[114:117] offset:18432
	ds_write_b128 v97, v[118:121] offset:23040
	ds_write_b128 v97, v[122:125] offset:27648
	ds_write_b128 v97, v[126:129] offset:32256
	ds_write_b128 v97, v[130:133] offset:36864
	ds_write_b128 v97, v[134:137] offset:41472
	v_lshl_add_u64 v[118:119], v[180:181], 0, s[2:3]
	s_waitcnt lgkmcnt(0)
	s_barrier
	v_lshl_add_u64 v[102:103], v[118:119], 0, s[22:23]
	global_load_dwordx4 v[98:101], v[102:103], off
	v_lshl_add_u64 v[106:107], v[118:119], 0, s[26:27]
	global_load_dwordx4 v[102:105], v[106:107], off
	v_lshl_add_u64 v[110:111], v[118:119], 0, s[48:49]
	global_load_dwordx4 v[106:109], v[110:111], off
	v_lshl_add_u64 v[114:115], v[118:119], 0, s[12:13]
	global_load_dwordx4 v[110:113], v[114:115], off
	v_lshl_add_u64 v[120:121], v[118:119], 0, s[6:7]
	global_load_dwordx4 v[114:117], v[120:121], off
	s_mov_b64 s[6:7], 0xa0180
	v_lshl_add_u64 v[122:123], v[118:119], 0, s[6:7]
	global_load_dwordx4 v[118:121], v[122:123], off
	v_lshl_add_u64 v[134:135], v[182:183], 0, s[2:3]
	v_mfma_f32_32x32x16_bf16 v[80:95], v[186:189], v[198:201], v[80:95]
	v_lshl_add_u64 v[126:127], v[134:135], 0, s[22:23]
	global_load_dwordx4 v[122:125], v[126:127], off
	v_lshl_add_u64 v[130:131], v[134:135], 0, s[26:27]
	global_load_dwordx4 v[126:129], v[130:131], off
	v_lshl_add_u64 v[136:137], v[134:135], 0, s[48:49]
	global_load_dwordx4 v[130:133], v[136:137], off
	s_mov_b32 s6, s5
	v_mfma_f32_32x32x16_bf16 v[64:79], v[186:189], v[202:205], v[64:79]
	v_lshl_add_u64 v[186:187], v[134:135], 0, s[12:13]
	global_load_dwordx4 v[134:137], v[186:187], off
	v_mfma_f32_32x32x16_bf16 v[48:63], v[190:193], v[198:201], v[48:63]
	v_mfma_f32_32x32x16_bf16 v[32:47], v[190:193], v[202:205], v[32:47]
	v_mfma_f32_32x32x16_bf16 v[16:31], v[194:197], v[198:201], v[16:31]
	v_mfma_f32_32x32x16_bf16 v[0:15], v[194:197], v[202:205], v[0:15]
	ds_read_b128 v[186:189], v179 offset:4608
	ds_read_b128 v[190:193], v179 offset:9216
	ds_read_b128 v[194:197], v184 offset:32256
	ds_read_b128 v[198:201], v179
	ds_read_b128 v[202:205], v179 offset:32
	ds_read_b128 v[206:209], v184 offset:27648
	ds_read_b128 v[210:213], v184 offset:27680
	s_waitcnt lgkmcnt(0)
	v_mfma_f32_32x32x16_bf16 v[80:95], v[198:201], v[206:209], v[80:95]
	v_mfma_f32_32x32x16_bf16 v[64:79], v[198:201], v[194:197], v[64:79]
	v_mfma_f32_32x32x16_bf16 v[48:63], v[186:189], v[206:209], v[48:63]
	v_mfma_f32_32x32x16_bf16 v[32:47], v[186:189], v[194:197], v[32:47]
	v_mfma_f32_32x32x16_bf16 v[16:31], v[190:193], v[206:209], v[16:31]
	v_mfma_f32_32x32x16_bf16 v[0:15], v[190:193], v[194:197], v[0:15]
	ds_read_b128 v[186:189], v179 offset:4640
	ds_read_b128 v[190:193], v179 offset:9248
	ds_read_b128 v[194:197], v184 offset:32288
	v_mfma_f32_32x32x16_bf16 v[80:95], v[202:205], v[210:213], v[80:95]
	s_waitcnt lgkmcnt(0)
	v_mfma_f32_32x32x16_bf16 v[64:79], v[202:205], v[194:197], v[64:79]
	v_mfma_f32_32x32x16_bf16 v[48:63], v[186:189], v[210:213], v[48:63]
	v_mfma_f32_32x32x16_bf16 v[32:47], v[186:189], v[194:197], v[32:47]
	v_mfma_f32_32x32x16_bf16 v[16:31], v[190:193], v[210:213], v[16:31]
	v_mfma_f32_32x32x16_bf16 v[0:15], v[190:193], v[194:197], v[0:15]
	ds_read_b128 v[186:189], v179 offset:64
	ds_read_b128 v[190:193], v179 offset:4672
	ds_read_b128 v[194:197], v179 offset:9280
	ds_read_b128 v[198:201], v184 offset:27712
	ds_read_b128 v[202:205], v184 offset:32320
	s_waitcnt lgkmcnt(0)
	v_mfma_f32_32x32x16_bf16 v[80:95], v[186:189], v[198:201], v[80:95]
	v_mfma_f32_32x32x16_bf16 v[64:79], v[186:189], v[202:205], v[64:79]
	v_mfma_f32_32x32x16_bf16 v[48:63], v[190:193], v[198:201], v[48:63]
	v_mfma_f32_32x32x16_bf16 v[32:47], v[190:193], v[202:205], v[32:47]
	v_mfma_f32_32x32x16_bf16 v[16:31], v[194:197], v[198:201], v[16:31]
	v_mfma_f32_32x32x16_bf16 v[0:15], v[194:197], v[202:205], v[0:15]
	ds_read_b128 v[186:189], v179 offset:96
	ds_read_b128 v[190:193], v179 offset:4704
	ds_read_b128 v[194:197], v179 offset:9312
	ds_read_b128 v[198:201], v184 offset:27744
	ds_read_b128 v[202:205], v184 offset:32352
	s_waitcnt vmcnt(10)
	s_waitcnt lgkmcnt(0)
	s_barrier
	ds_write_b128 v97, v[138:141]
	ds_write_b128 v97, v[142:145] offset:4608
	ds_write_b128 v97, v[146:149] offset:9216
	ds_write_b128 v97, v[150:153] offset:13824
	ds_write_b128 v97, v[154:157] offset:18432
	ds_write_b128 v97, v[158:161] offset:23040
	ds_write_b128 v97, v[162:165] offset:27648
	ds_write_b128 v97, v[166:169] offset:32256
	ds_write_b128 v97, v[170:173] offset:36864
	ds_write_b128 v97, v[174:177] offset:41472
	s_waitcnt lgkmcnt(0)
	v_mfma_f32_32x32x16_bf16 v[80:95], v[186:189], v[198:201], v[80:95]
	s_barrier
	v_mfma_f32_32x32x16_bf16 v[64:79], v[186:189], v[202:205], v[64:79]
	v_mfma_f32_32x32x16_bf16 v[48:63], v[190:193], v[198:201], v[48:63]
	v_mfma_f32_32x32x16_bf16 v[32:47], v[190:193], v[202:205], v[32:47]
	v_mfma_f32_32x32x16_bf16 v[16:31], v[194:197], v[198:201], v[16:31]
	v_mfma_f32_32x32x16_bf16 v[0:15], v[194:197], v[202:205], v[0:15]
	s_cbranch_vccnz .LBB0_778
	s_waitcnt vmcnt(0)
	s_lshl_b64 s[4:5], s[0:1], 10
	s_lshl_b64 s[10:11], s[0:1], 11
	s_lshl_b64 s[6:7], s[8:9], 1
	s_add_u32 s12, s37, s10
	s_addc_u32 s13, s38, s11
	s_add_u32 s12, s12, s6
	s_addc_u32 s13, s13, s7
	s_add_u32 s0, s43, s10
	s_addc_u32 s1, s44, s11
	s_add_u32 s0, s0, s6
	s_addc_u32 s1, s1, s7
	s_add_u32 s10, s17, s10
	s_addc_u32 s11, s20, s11
	s_lshl_b64 s[8:9], s[8:9], 11
	s_add_u32 s8, s35, s8
	s_addc_u32 s9, s36, s9
	v_and_b32_e32 v97, 0x5f, v244
	v_lshrrev_b32_e32 v98, 7, v244
	v_mul_u32_u24_e32 v98, 0x60, v98
	v_lshrrev_b32_e32 v99, 3, v244
	v_and_or_b32 v98, v99, 4, v98
	v_lshl_or_b32 v99, v98, 10, v97
	v_lshlrev_b32_e32 v99, 1, v99
	s_mov_b64 s[52:53], s[12:13]
	s_mov_b64 s[12:13], s[52:53]
	global_load_ushort v100, v99, s[12:13]
	s_add_u32 s12, s12, 0x800
	s_addc_u32 s13, s13, 0
	global_load_ushort v101, v99, s[12:13]
	s_add_u32 s12, s12, 0x800
	s_addc_u32 s13, s13, 0
	global_load_ushort v102, v99, s[12:13]
	s_add_u32 s12, s12, 0x800
	s_addc_u32 s13, s13, 0
	global_load_ushort v103, v99, s[12:13]
	s_add_u32 s12, s12, 0x2800
	s_addc_u32 s13, s13, 0
	global_load_ushort v104, v99, s[12:13]
	s_add_u32 s12, s12, 0x800
	s_addc_u32 s13, s13, 0
	global_load_ushort v105, v99, s[12:13]
	s_add_u32 s12, s12, 0x800
	s_addc_u32 s13, s13, 0
	global_load_ushort v106, v99, s[12:13]
	s_add_u32 s12, s12, 0x800
	s_addc_u32 s13, s13, 0
	global_load_ushort v107, v99, s[12:13]
	s_add_u32 s12, s12, 0x2800
	s_addc_u32 s13, s13, 0
	global_load_ushort v108, v99, s[12:13]
	s_add_u32 s12, s12, 0x800
	s_addc_u32 s13, s13, 0
	global_load_ushort v109, v99, s[12:13]
	s_add_u32 s12, s12, 0x800
	s_addc_u32 s13, s13, 0
	global_load_ushort v110, v99, s[12:13]
	s_add_u32 s12, s12, 0x800
	s_addc_u32 s13, s13, 0
	global_load_ushort v111, v99, s[12:13]
	s_add_u32 s12, s12, 0x2800
	s_addc_u32 s13, s13, 0
	global_load_ushort v112, v99, s[12:13]
	s_add_u32 s12, s12, 0x800
	s_addc_u32 s13, s13, 0
	global_load_ushort v113, v99, s[12:13]
	s_add_u32 s12, s12, 0x800
	s_addc_u32 s13, s13, 0
	global_load_ushort v114, v99, s[12:13]
	s_add_u32 s12, s12, 0x800
	s_addc_u32 s13, s13, 0
	global_load_ushort v115, v99, s[12:13]
	s_add_u32 s12, s12, 0x2800
	s_addc_u32 s13, s13, 0
	global_load_ushort v116, v99, s[12:13]
	s_add_u32 s12, s12, 0x800
	s_addc_u32 s13, s13, 0
	global_load_ushort v117, v99, s[12:13]
	s_add_u32 s12, s12, 0x800
	s_addc_u32 s13, s13, 0
	global_load_ushort v118, v99, s[12:13]
	s_add_u32 s12, s12, 0x800
	s_addc_u32 s13, s13, 0
	global_load_ushort v119, v99, s[12:13]
	s_add_u32 s12, s12, 0x2800
	s_addc_u32 s13, s13, 0
	global_load_ushort v120, v99, s[12:13]
	s_add_u32 s12, s12, 0x800
	s_addc_u32 s13, s13, 0
	global_load_ushort v121, v99, s[12:13]
	s_add_u32 s12, s12, 0x800
	s_addc_u32 s13, s13, 0
	global_load_ushort v122, v99, s[12:13]
	s_add_u32 s12, s12, 0x800
	s_addc_u32 s13, s13, 0
	global_load_ushort v123, v99, s[12:13]
	s_add_u32 s12, s12, 0x2800
	s_addc_u32 s13, s13, 0
	global_load_ushort v124, v99, s[12:13]
	s_add_u32 s12, s12, 0x800
	s_addc_u32 s13, s13, 0
	global_load_ushort v125, v99, s[12:13]
	s_add_u32 s12, s12, 0x800
	s_addc_u32 s13, s13, 0
	global_load_ushort v126, v99, s[12:13]
	s_add_u32 s12, s12, 0x800
	s_addc_u32 s13, s13, 0
	global_load_ushort v127, v99, s[12:13]
	s_add_u32 s12, s12, 0x2800
	s_addc_u32 s13, s13, 0
	global_load_ushort v128, v99, s[12:13]
	s_add_u32 s12, s12, 0x800
	s_addc_u32 s13, s13, 0
	global_load_ushort v129, v99, s[12:13]
	s_add_u32 s12, s12, 0x800
	s_addc_u32 s13, s13, 0
	global_load_ushort v130, v99, s[12:13]
	s_add_u32 s12, s12, 0x800
	s_addc_u32 s13, s13, 0
	global_load_ushort v131, v99, s[12:13]
	s_add_u32 s12, s12, 0x2800
	s_addc_u32 s13, s13, 0
	global_load_ushort v132, v99, s[12:13]
	s_add_u32 s12, s12, 0x800
	s_addc_u32 s13, s13, 0
	global_load_ushort v133, v99, s[12:13]
	s_add_u32 s12, s12, 0x800
	s_addc_u32 s13, s13, 0
	global_load_ushort v134, v99, s[12:13]
	s_add_u32 s12, s12, 0x800
	s_addc_u32 s13, s13, 0
	global_load_ushort v135, v99, s[12:13]
	s_add_u32 s12, s12, 0x2800
	s_addc_u32 s13, s13, 0
	global_load_ushort v136, v99, s[12:13]
	s_add_u32 s12, s12, 0x800
	s_addc_u32 s13, s13, 0
	global_load_ushort v137, v99, s[12:13]
	s_add_u32 s12, s12, 0x800
	s_addc_u32 s13, s13, 0
	global_load_ushort v138, v99, s[12:13]
	s_add_u32 s12, s12, 0x800
	s_addc_u32 s13, s13, 0
	global_load_ushort v139, v99, s[12:13]
	s_add_u32 s12, s12, 0x2800
	s_addc_u32 s13, s13, 0
	global_load_ushort v140, v99, s[12:13]
	s_add_u32 s12, s12, 0x800
	s_addc_u32 s13, s13, 0
	global_load_ushort v141, v99, s[12:13]
	s_add_u32 s12, s12, 0x800
	s_addc_u32 s13, s13, 0
	global_load_ushort v142, v99, s[12:13]
	s_add_u32 s12, s12, 0x800
	s_addc_u32 s13, s13, 0
	global_load_ushort v143, v99, s[12:13]
	s_add_u32 s12, s12, 0x2800
	s_addc_u32 s13, s13, 0
	global_load_ushort v144, v99, s[12:13]
	s_add_u32 s12, s12, 0x800
	s_addc_u32 s13, s13, 0
	global_load_ushort v145, v99, s[12:13]
	s_add_u32 s12, s12, 0x800
	s_addc_u32 s13, s13, 0
	global_load_ushort v146, v99, s[12:13]
	s_add_u32 s12, s12, 0x800
	s_addc_u32 s13, s13, 0
	global_load_ushort v147, v99, s[12:13]
	s_waitcnt vmcnt(0)
	v_lshlrev_b32_e32 v100, 16, v100
	v_mul_f32_e32 v100, v80, v100
	v_cvt_pk_bf16_f32 v100, v100, v100
	v_lshlrev_b32_e32 v101, 16, v101
	v_mul_f32_e32 v101, v81, v101
	v_cvt_pk_bf16_f32 v101, v101, v101
	v_lshlrev_b32_e32 v102, 16, v102
	v_mul_f32_e32 v102, v82, v102
	v_cvt_pk_bf16_f32 v102, v102, v102
	v_lshlrev_b32_e32 v103, 16, v103
	v_mul_f32_e32 v103, v83, v103
	v_cvt_pk_bf16_f32 v103, v103, v103
	v_lshlrev_b32_e32 v104, 16, v104
	v_mul_f32_e32 v104, v84, v104
	v_cvt_pk_bf16_f32 v104, v104, v104
	v_lshlrev_b32_e32 v105, 16, v105
	v_mul_f32_e32 v105, v85, v105
	v_cvt_pk_bf16_f32 v105, v105, v105
	v_lshlrev_b32_e32 v106, 16, v106
	v_mul_f32_e32 v106, v86, v106
	v_cvt_pk_bf16_f32 v106, v106, v106
	v_lshlrev_b32_e32 v107, 16, v107
	v_mul_f32_e32 v107, v87, v107
	v_cvt_pk_bf16_f32 v107, v107, v107
	v_lshlrev_b32_e32 v108, 16, v108
	v_mul_f32_e32 v108, v88, v108
	v_cvt_pk_bf16_f32 v108, v108, v108
	v_lshlrev_b32_e32 v109, 16, v109
	v_mul_f32_e32 v109, v89, v109
	v_cvt_pk_bf16_f32 v109, v109, v109
	v_lshlrev_b32_e32 v110, 16, v110
	v_mul_f32_e32 v110, v90, v110
	v_cvt_pk_bf16_f32 v110, v110, v110
	v_lshlrev_b32_e32 v111, 16, v111
	v_mul_f32_e32 v111, v91, v111
	v_cvt_pk_bf16_f32 v111, v111, v111
	v_lshlrev_b32_e32 v112, 16, v112
	v_mul_f32_e32 v112, v92, v112
	v_cvt_pk_bf16_f32 v112, v112, v112
	v_lshlrev_b32_e32 v113, 16, v113
	v_mul_f32_e32 v113, v93, v113
	v_cvt_pk_bf16_f32 v113, v113, v113
	v_lshlrev_b32_e32 v114, 16, v114
	v_mul_f32_e32 v114, v94, v114
	v_cvt_pk_bf16_f32 v114, v114, v114
	v_lshlrev_b32_e32 v115, 16, v115
	v_mul_f32_e32 v115, v95, v115
	v_cvt_pk_bf16_f32 v115, v115, v115
	v_lshlrev_b32_e32 v116, 16, v116
	v_mul_f32_e32 v116, v48, v116
	v_cvt_pk_bf16_f32 v116, v116, v116
	v_lshlrev_b32_e32 v117, 16, v117
	v_mul_f32_e32 v117, v49, v117
	v_cvt_pk_bf16_f32 v117, v117, v117
	v_lshlrev_b32_e32 v118, 16, v118
	v_mul_f32_e32 v118, v50, v118
	v_cvt_pk_bf16_f32 v118, v118, v118
	v_lshlrev_b32_e32 v119, 16, v119
	v_mul_f32_e32 v119, v51, v119
	v_cvt_pk_bf16_f32 v119, v119, v119
	v_lshlrev_b32_e32 v120, 16, v120
	v_mul_f32_e32 v120, v52, v120
	v_cvt_pk_bf16_f32 v120, v120, v120
	v_lshlrev_b32_e32 v121, 16, v121
	v_mul_f32_e32 v121, v53, v121
	v_cvt_pk_bf16_f32 v121, v121, v121
	v_lshlrev_b32_e32 v122, 16, v122
	v_mul_f32_e32 v122, v54, v122
	v_cvt_pk_bf16_f32 v122, v122, v122
	v_lshlrev_b32_e32 v123, 16, v123
	v_mul_f32_e32 v123, v55, v123
	v_cvt_pk_bf16_f32 v123, v123, v123
	v_lshlrev_b32_e32 v124, 16, v124
	v_mul_f32_e32 v124, v56, v124
	v_cvt_pk_bf16_f32 v124, v124, v124
	v_lshlrev_b32_e32 v125, 16, v125
	v_mul_f32_e32 v125, v57, v125
	v_cvt_pk_bf16_f32 v125, v125, v125
	v_lshlrev_b32_e32 v126, 16, v126
	v_mul_f32_e32 v126, v58, v126
	v_cvt_pk_bf16_f32 v126, v126, v126
	v_lshlrev_b32_e32 v127, 16, v127
	v_mul_f32_e32 v127, v59, v127
	v_cvt_pk_bf16_f32 v127, v127, v127
	v_lshlrev_b32_e32 v128, 16, v128
	v_mul_f32_e32 v128, v60, v128
	v_cvt_pk_bf16_f32 v128, v128, v128
	v_lshlrev_b32_e32 v129, 16, v129
	v_mul_f32_e32 v129, v61, v129
	v_cvt_pk_bf16_f32 v129, v129, v129
	v_lshlrev_b32_e32 v130, 16, v130
	v_mul_f32_e32 v130, v62, v130
	v_cvt_pk_bf16_f32 v130, v130, v130
	v_lshlrev_b32_e32 v131, 16, v131
	v_mul_f32_e32 v131, v63, v131
	v_cvt_pk_bf16_f32 v131, v131, v131
	v_lshlrev_b32_e32 v132, 16, v132
	v_mul_f32_e32 v132, v16, v132
	v_cvt_pk_bf16_f32 v132, v132, v132
	v_lshlrev_b32_e32 v133, 16, v133
	v_mul_f32_e32 v133, v17, v133
	v_cvt_pk_bf16_f32 v133, v133, v133
	v_lshlrev_b32_e32 v134, 16, v134
	v_mul_f32_e32 v134, v18, v134
	v_cvt_pk_bf16_f32 v134, v134, v134
	v_lshlrev_b32_e32 v135, 16, v135
	v_mul_f32_e32 v135, v19, v135
	v_cvt_pk_bf16_f32 v135, v135, v135
	v_lshlrev_b32_e32 v136, 16, v136
	v_mul_f32_e32 v136, v20, v136
	v_cvt_pk_bf16_f32 v136, v136, v136
	v_lshlrev_b32_e32 v137, 16, v137
	v_mul_f32_e32 v137, v21, v137
	v_cvt_pk_bf16_f32 v137, v137, v137
	v_lshlrev_b32_e32 v138, 16, v138
	v_mul_f32_e32 v138, v22, v138
	v_cvt_pk_bf16_f32 v138, v138, v138
	v_lshlrev_b32_e32 v139, 16, v139
	v_mul_f32_e32 v139, v23, v139
	v_cvt_pk_bf16_f32 v139, v139, v139
	v_lshlrev_b32_e32 v140, 16, v140
	v_mul_f32_e32 v140, v24, v140
	v_cvt_pk_bf16_f32 v140, v140, v140
	v_lshlrev_b32_e32 v141, 16, v141
	v_mul_f32_e32 v141, v25, v141
	v_cvt_pk_bf16_f32 v141, v141, v141
	v_lshlrev_b32_e32 v142, 16, v142
	v_mul_f32_e32 v142, v26, v142
	v_cvt_pk_bf16_f32 v142, v142, v142
	v_lshlrev_b32_e32 v143, 16, v143
	v_mul_f32_e32 v143, v27, v143
	v_cvt_pk_bf16_f32 v143, v143, v143
	v_lshlrev_b32_e32 v144, 16, v144
	v_mul_f32_e32 v144, v28, v144
	v_cvt_pk_bf16_f32 v144, v144, v144
	v_lshlrev_b32_e32 v145, 16, v145
	v_mul_f32_e32 v145, v29, v145
	v_cvt_pk_bf16_f32 v145, v145, v145
	v_lshlrev_b32_e32 v146, 16, v146
	v_mul_f32_e32 v146, v30, v146
	v_cvt_pk_bf16_f32 v146, v146, v146
	v_lshlrev_b32_e32 v147, 16, v147
	v_mul_f32_e32 v147, v31, v147
	v_cvt_pk_bf16_f32 v147, v147, v147
	s_mov_b64 s[50:51], s[0:1]
	global_store_short v99, v100, s[50:51]
	s_add_u32 s50, s50, 0x800
	s_addc_u32 s51, s51, 0
	global_store_short v99, v101, s[50:51]
	s_add_u32 s50, s50, 0x800
	s_addc_u32 s51, s51, 0
	global_store_short v99, v102, s[50:51]
	s_add_u32 s50, s50, 0x800
	s_addc_u32 s51, s51, 0
	global_store_short v99, v103, s[50:51]
	s_add_u32 s50, s50, 0x2800
	s_addc_u32 s51, s51, 0
	global_store_short v99, v104, s[50:51]
	s_add_u32 s50, s50, 0x800
	s_addc_u32 s51, s51, 0
	global_store_short v99, v105, s[50:51]
	s_add_u32 s50, s50, 0x800
	s_addc_u32 s51, s51, 0
	global_store_short v99, v106, s[50:51]
	s_add_u32 s50, s50, 0x800
	s_addc_u32 s51, s51, 0
	global_store_short v99, v107, s[50:51]
	s_add_u32 s50, s50, 0x2800
	s_addc_u32 s51, s51, 0
	global_store_short v99, v108, s[50:51]
	s_add_u32 s50, s50, 0x800
	s_addc_u32 s51, s51, 0
	global_store_short v99, v109, s[50:51]
	s_add_u32 s50, s50, 0x800
	s_addc_u32 s51, s51, 0
	global_store_short v99, v110, s[50:51]
	s_add_u32 s50, s50, 0x800
	s_addc_u32 s51, s51, 0
	global_store_short v99, v111, s[50:51]
	s_add_u32 s50, s50, 0x2800
	s_addc_u32 s51, s51, 0
	global_store_short v99, v112, s[50:51]
	s_add_u32 s50, s50, 0x800
	s_addc_u32 s51, s51, 0
	global_store_short v99, v113, s[50:51]
	s_add_u32 s50, s50, 0x800
	s_addc_u32 s51, s51, 0
	global_store_short v99, v114, s[50:51]
	s_add_u32 s50, s50, 0x800
	s_addc_u32 s51, s51, 0
	global_store_short v99, v115, s[50:51]
	s_add_u32 s50, s50, 0x2800
	s_addc_u32 s51, s51, 0
	global_store_short v99, v116, s[50:51]
	s_add_u32 s50, s50, 0x800
	s_addc_u32 s51, s51, 0
	global_store_short v99, v117, s[50:51]
	s_add_u32 s50, s50, 0x800
	s_addc_u32 s51, s51, 0
	global_store_short v99, v118, s[50:51]
	s_add_u32 s50, s50, 0x800
	s_addc_u32 s51, s51, 0
	global_store_short v99, v119, s[50:51]
	s_add_u32 s50, s50, 0x2800
	s_addc_u32 s51, s51, 0
	global_store_short v99, v120, s[50:51]
	s_add_u32 s50, s50, 0x800
	s_addc_u32 s51, s51, 0
	global_store_short v99, v121, s[50:51]
	s_add_u32 s50, s50, 0x800
	s_addc_u32 s51, s51, 0
	global_store_short v99, v122, s[50:51]
	s_add_u32 s50, s50, 0x800
	s_addc_u32 s51, s51, 0
	global_store_short v99, v123, s[50:51]
	s_add_u32 s50, s50, 0x2800
	s_addc_u32 s51, s51, 0
	global_store_short v99, v124, s[50:51]
	s_add_u32 s50, s50, 0x800
	s_addc_u32 s51, s51, 0
	global_store_short v99, v125, s[50:51]
	s_add_u32 s50, s50, 0x800
	s_addc_u32 s51, s51, 0
	global_store_short v99, v126, s[50:51]
	s_add_u32 s50, s50, 0x800
	s_addc_u32 s51, s51, 0
	global_store_short v99, v127, s[50:51]
	s_add_u32 s50, s50, 0x2800
	s_addc_u32 s51, s51, 0
	global_store_short v99, v128, s[50:51]
	s_add_u32 s50, s50, 0x800
	s_addc_u32 s51, s51, 0
	global_store_short v99, v129, s[50:51]
	s_add_u32 s50, s50, 0x800
	s_addc_u32 s51, s51, 0
	global_store_short v99, v130, s[50:51]
	s_add_u32 s50, s50, 0x800
	s_addc_u32 s51, s51, 0
	global_store_short v99, v131, s[50:51]
	s_add_u32 s50, s50, 0x2800
	s_addc_u32 s51, s51, 0
	global_store_short v99, v132, s[50:51]
	s_add_u32 s50, s50, 0x800
	s_addc_u32 s51, s51, 0
	global_store_short v99, v133, s[50:51]
	s_add_u32 s50, s50, 0x800
	s_addc_u32 s51, s51, 0
	global_store_short v99, v134, s[50:51]
	s_add_u32 s50, s50, 0x800
	s_addc_u32 s51, s51, 0
	global_store_short v99, v135, s[50:51]
	s_add_u32 s50, s50, 0x2800
	s_addc_u32 s51, s51, 0
	global_store_short v99, v136, s[50:51]
	s_add_u32 s50, s50, 0x800
	s_addc_u32 s51, s51, 0
	global_store_short v99, v137, s[50:51]
	s_add_u32 s50, s50, 0x800
	s_addc_u32 s51, s51, 0
	global_store_short v99, v138, s[50:51]
	s_add_u32 s50, s50, 0x800
	s_addc_u32 s51, s51, 0
	global_store_short v99, v139, s[50:51]
	s_add_u32 s50, s50, 0x2800
	s_addc_u32 s51, s51, 0
	global_store_short v99, v140, s[50:51]
	s_add_u32 s50, s50, 0x800
	s_addc_u32 s51, s51, 0
	global_store_short v99, v141, s[50:51]
	s_add_u32 s50, s50, 0x800
	s_addc_u32 s51, s51, 0
	global_store_short v99, v142, s[50:51]
	s_add_u32 s50, s50, 0x800
	s_addc_u32 s51, s51, 0
	global_store_short v99, v143, s[50:51]
	s_add_u32 s50, s50, 0x2800
	s_addc_u32 s51, s51, 0
	global_store_short v99, v144, s[50:51]
	s_add_u32 s50, s50, 0x800
	s_addc_u32 s51, s51, 0
	global_store_short v99, v145, s[50:51]
	s_add_u32 s50, s50, 0x800
	s_addc_u32 s51, s51, 0
	global_store_short v99, v146, s[50:51]
	s_add_u32 s50, s50, 0x800
	s_addc_u32 s51, s51, 0
	global_store_short v99, v147, s[50:51]
	s_mov_b64 s[12:13], s[52:53]
	global_load_ushort v100, v99, s[12:13] offset:64
	s_add_u32 s12, s12, 0x800
	s_addc_u32 s13, s13, 0
	global_load_ushort v101, v99, s[12:13] offset:64
	s_add_u32 s12, s12, 0x800
	s_addc_u32 s13, s13, 0
	global_load_ushort v102, v99, s[12:13] offset:64
	s_add_u32 s12, s12, 0x800
	s_addc_u32 s13, s13, 0
	global_load_ushort v103, v99, s[12:13] offset:64
	s_add_u32 s12, s12, 0x2800
	s_addc_u32 s13, s13, 0
	global_load_ushort v104, v99, s[12:13] offset:64
	s_add_u32 s12, s12, 0x800
	s_addc_u32 s13, s13, 0
	global_load_ushort v105, v99, s[12:13] offset:64
	s_add_u32 s12, s12, 0x800
	s_addc_u32 s13, s13, 0
	global_load_ushort v106, v99, s[12:13] offset:64
	s_add_u32 s12, s12, 0x800
	s_addc_u32 s13, s13, 0
	global_load_ushort v107, v99, s[12:13] offset:64
	s_add_u32 s12, s12, 0x2800
	s_addc_u32 s13, s13, 0
	global_load_ushort v108, v99, s[12:13] offset:64
	s_add_u32 s12, s12, 0x800
	s_addc_u32 s13, s13, 0
	global_load_ushort v109, v99, s[12:13] offset:64
	s_add_u32 s12, s12, 0x800
	s_addc_u32 s13, s13, 0
	global_load_ushort v110, v99, s[12:13] offset:64
	s_add_u32 s12, s12, 0x800
	s_addc_u32 s13, s13, 0
	global_load_ushort v111, v99, s[12:13] offset:64
	s_add_u32 s12, s12, 0x2800
	s_addc_u32 s13, s13, 0
	global_load_ushort v112, v99, s[12:13] offset:64
	s_add_u32 s12, s12, 0x800
	s_addc_u32 s13, s13, 0
	global_load_ushort v113, v99, s[12:13] offset:64
	s_add_u32 s12, s12, 0x800
	s_addc_u32 s13, s13, 0
	global_load_ushort v114, v99, s[12:13] offset:64
	s_add_u32 s12, s12, 0x800
	s_addc_u32 s13, s13, 0
	global_load_ushort v115, v99, s[12:13] offset:64
	s_add_u32 s12, s12, 0x2800
	s_addc_u32 s13, s13, 0
	global_load_ushort v116, v99, s[12:13] offset:64
	s_add_u32 s12, s12, 0x800
	s_addc_u32 s13, s13, 0
	global_load_ushort v117, v99, s[12:13] offset:64
	s_add_u32 s12, s12, 0x800
	s_addc_u32 s13, s13, 0
	global_load_ushort v118, v99, s[12:13] offset:64
	s_add_u32 s12, s12, 0x800
	s_addc_u32 s13, s13, 0
	global_load_ushort v119, v99, s[12:13] offset:64
	s_add_u32 s12, s12, 0x2800
	s_addc_u32 s13, s13, 0
	global_load_ushort v120, v99, s[12:13] offset:64
	s_add_u32 s12, s12, 0x800
	s_addc_u32 s13, s13, 0
	global_load_ushort v121, v99, s[12:13] offset:64
	s_add_u32 s12, s12, 0x800
	s_addc_u32 s13, s13, 0
	global_load_ushort v122, v99, s[12:13] offset:64
	s_add_u32 s12, s12, 0x800
	s_addc_u32 s13, s13, 0
	global_load_ushort v123, v99, s[12:13] offset:64
	s_add_u32 s12, s12, 0x2800
	s_addc_u32 s13, s13, 0
	global_load_ushort v124, v99, s[12:13] offset:64
	s_add_u32 s12, s12, 0x800
	s_addc_u32 s13, s13, 0
	global_load_ushort v125, v99, s[12:13] offset:64
	s_add_u32 s12, s12, 0x800
	s_addc_u32 s13, s13, 0
	global_load_ushort v126, v99, s[12:13] offset:64
	s_add_u32 s12, s12, 0x800
	s_addc_u32 s13, s13, 0
	global_load_ushort v127, v99, s[12:13] offset:64
	s_add_u32 s12, s12, 0x2800
	s_addc_u32 s13, s13, 0
	global_load_ushort v128, v99, s[12:13] offset:64
	s_add_u32 s12, s12, 0x800
	s_addc_u32 s13, s13, 0
	global_load_ushort v129, v99, s[12:13] offset:64
	s_add_u32 s12, s12, 0x800
	s_addc_u32 s13, s13, 0
	global_load_ushort v130, v99, s[12:13] offset:64
	s_add_u32 s12, s12, 0x800
	s_addc_u32 s13, s13, 0
	global_load_ushort v131, v99, s[12:13] offset:64
	s_add_u32 s12, s12, 0x2800
	s_addc_u32 s13, s13, 0
	global_load_ushort v132, v99, s[12:13] offset:64
	s_add_u32 s12, s12, 0x800
	s_addc_u32 s13, s13, 0
	global_load_ushort v133, v99, s[12:13] offset:64
	s_add_u32 s12, s12, 0x800
	s_addc_u32 s13, s13, 0
	global_load_ushort v134, v99, s[12:13] offset:64
	s_add_u32 s12, s12, 0x800
	s_addc_u32 s13, s13, 0
	global_load_ushort v135, v99, s[12:13] offset:64
	s_add_u32 s12, s12, 0x2800
	s_addc_u32 s13, s13, 0
	global_load_ushort v136, v99, s[12:13] offset:64
	s_add_u32 s12, s12, 0x800
	s_addc_u32 s13, s13, 0
	global_load_ushort v137, v99, s[12:13] offset:64
	s_add_u32 s12, s12, 0x800
	s_addc_u32 s13, s13, 0
	global_load_ushort v138, v99, s[12:13] offset:64
	s_add_u32 s12, s12, 0x800
	s_addc_u32 s13, s13, 0
	global_load_ushort v139, v99, s[12:13] offset:64
	s_add_u32 s12, s12, 0x2800
	s_addc_u32 s13, s13, 0
	global_load_ushort v140, v99, s[12:13] offset:64
	s_add_u32 s12, s12, 0x800
	s_addc_u32 s13, s13, 0
	global_load_ushort v141, v99, s[12:13] offset:64
	s_add_u32 s12, s12, 0x800
	s_addc_u32 s13, s13, 0
	global_load_ushort v142, v99, s[12:13] offset:64
	s_add_u32 s12, s12, 0x800
	s_addc_u32 s13, s13, 0
	global_load_ushort v143, v99, s[12:13] offset:64
	s_add_u32 s12, s12, 0x2800
	s_addc_u32 s13, s13, 0
	global_load_ushort v144, v99, s[12:13] offset:64
	s_add_u32 s12, s12, 0x800
	s_addc_u32 s13, s13, 0
	global_load_ushort v145, v99, s[12:13] offset:64
	s_add_u32 s12, s12, 0x800
	s_addc_u32 s13, s13, 0
	global_load_ushort v146, v99, s[12:13] offset:64
	s_add_u32 s12, s12, 0x800
	s_addc_u32 s13, s13, 0
	global_load_ushort v147, v99, s[12:13] offset:64
	s_waitcnt vmcnt(0)
	v_lshlrev_b32_e32 v100, 16, v100
	v_mul_f32_e32 v100, v64, v100
	v_cvt_pk_bf16_f32 v100, v100, v100
	v_lshlrev_b32_e32 v101, 16, v101
	v_mul_f32_e32 v101, v65, v101
	v_cvt_pk_bf16_f32 v101, v101, v101
	v_lshlrev_b32_e32 v102, 16, v102
	v_mul_f32_e32 v102, v66, v102
	v_cvt_pk_bf16_f32 v102, v102, v102
	v_lshlrev_b32_e32 v103, 16, v103
	v_mul_f32_e32 v103, v67, v103
	v_cvt_pk_bf16_f32 v103, v103, v103
	v_lshlrev_b32_e32 v104, 16, v104
	v_mul_f32_e32 v104, v68, v104
	v_cvt_pk_bf16_f32 v104, v104, v104
	v_lshlrev_b32_e32 v105, 16, v105
	v_mul_f32_e32 v105, v69, v105
	v_cvt_pk_bf16_f32 v105, v105, v105
	v_lshlrev_b32_e32 v106, 16, v106
	v_mul_f32_e32 v106, v70, v106
	v_cvt_pk_bf16_f32 v106, v106, v106
	v_lshlrev_b32_e32 v107, 16, v107
	v_mul_f32_e32 v107, v71, v107
	v_cvt_pk_bf16_f32 v107, v107, v107
	v_lshlrev_b32_e32 v108, 16, v108
	v_mul_f32_e32 v108, v72, v108
	v_cvt_pk_bf16_f32 v108, v108, v108
	v_lshlrev_b32_e32 v109, 16, v109
	v_mul_f32_e32 v109, v73, v109
	v_cvt_pk_bf16_f32 v109, v109, v109
	v_lshlrev_b32_e32 v110, 16, v110
	v_mul_f32_e32 v110, v74, v110
	v_cvt_pk_bf16_f32 v110, v110, v110
	v_lshlrev_b32_e32 v111, 16, v111
	v_mul_f32_e32 v111, v75, v111
	v_cvt_pk_bf16_f32 v111, v111, v111
	v_lshlrev_b32_e32 v112, 16, v112
	v_mul_f32_e32 v112, v76, v112
	v_cvt_pk_bf16_f32 v112, v112, v112
	v_lshlrev_b32_e32 v113, 16, v113
	v_mul_f32_e32 v113, v77, v113
	v_cvt_pk_bf16_f32 v113, v113, v113
	v_lshlrev_b32_e32 v114, 16, v114
	v_mul_f32_e32 v114, v78, v114
	v_cvt_pk_bf16_f32 v114, v114, v114
	v_lshlrev_b32_e32 v115, 16, v115
	v_mul_f32_e32 v115, v79, v115
	v_cvt_pk_bf16_f32 v115, v115, v115
	v_lshlrev_b32_e32 v116, 16, v116
	v_mul_f32_e32 v116, v32, v116
	v_cvt_pk_bf16_f32 v116, v116, v116
	v_lshlrev_b32_e32 v117, 16, v117
	v_mul_f32_e32 v117, v33, v117
	v_cvt_pk_bf16_f32 v117, v117, v117
	v_lshlrev_b32_e32 v118, 16, v118
	v_mul_f32_e32 v118, v34, v118
	v_cvt_pk_bf16_f32 v118, v118, v118
	v_lshlrev_b32_e32 v119, 16, v119
	v_mul_f32_e32 v119, v35, v119
	v_cvt_pk_bf16_f32 v119, v119, v119
	v_lshlrev_b32_e32 v120, 16, v120
	v_mul_f32_e32 v120, v36, v120
	v_cvt_pk_bf16_f32 v120, v120, v120
	v_lshlrev_b32_e32 v121, 16, v121
	v_mul_f32_e32 v121, v37, v121
	v_cvt_pk_bf16_f32 v121, v121, v121
	v_lshlrev_b32_e32 v122, 16, v122
	v_mul_f32_e32 v122, v38, v122
	v_cvt_pk_bf16_f32 v122, v122, v122
	v_lshlrev_b32_e32 v123, 16, v123
	v_mul_f32_e32 v123, v39, v123
	v_cvt_pk_bf16_f32 v123, v123, v123
	v_lshlrev_b32_e32 v124, 16, v124
	v_mul_f32_e32 v124, v40, v124
	v_cvt_pk_bf16_f32 v124, v124, v124
	v_lshlrev_b32_e32 v125, 16, v125
	v_mul_f32_e32 v125, v41, v125
	v_cvt_pk_bf16_f32 v125, v125, v125
	v_lshlrev_b32_e32 v126, 16, v126
	v_mul_f32_e32 v126, v42, v126
	v_cvt_pk_bf16_f32 v126, v126, v126
	v_lshlrev_b32_e32 v127, 16, v127
	v_mul_f32_e32 v127, v43, v127
	v_cvt_pk_bf16_f32 v127, v127, v127
	v_lshlrev_b32_e32 v128, 16, v128
	v_mul_f32_e32 v128, v44, v128
	v_cvt_pk_bf16_f32 v128, v128, v128
	v_lshlrev_b32_e32 v129, 16, v129
	v_mul_f32_e32 v129, v45, v129
	v_cvt_pk_bf16_f32 v129, v129, v129
	v_lshlrev_b32_e32 v130, 16, v130
	v_mul_f32_e32 v130, v46, v130
	v_cvt_pk_bf16_f32 v130, v130, v130
	v_lshlrev_b32_e32 v131, 16, v131
	v_mul_f32_e32 v131, v47, v131
	v_cvt_pk_bf16_f32 v131, v131, v131
	v_lshlrev_b32_e32 v132, 16, v132
	v_mul_f32_e32 v132, v0, v132
	v_cvt_pk_bf16_f32 v132, v132, v132
	v_lshlrev_b32_e32 v133, 16, v133
	v_mul_f32_e32 v133, v1, v133
	v_cvt_pk_bf16_f32 v133, v133, v133
	v_lshlrev_b32_e32 v134, 16, v134
	v_mul_f32_e32 v134, v2, v134
	v_cvt_pk_bf16_f32 v134, v134, v134
	v_lshlrev_b32_e32 v135, 16, v135
	v_mul_f32_e32 v135, v3, v135
	v_cvt_pk_bf16_f32 v135, v135, v135
	v_lshlrev_b32_e32 v136, 16, v136
	v_mul_f32_e32 v136, v4, v136
	v_cvt_pk_bf16_f32 v136, v136, v136
	v_lshlrev_b32_e32 v137, 16, v137
	v_mul_f32_e32 v137, v5, v137
	v_cvt_pk_bf16_f32 v137, v137, v137
	v_lshlrev_b32_e32 v138, 16, v138
	v_mul_f32_e32 v138, v6, v138
	v_cvt_pk_bf16_f32 v138, v138, v138
	v_lshlrev_b32_e32 v139, 16, v139
	v_mul_f32_e32 v139, v7, v139
	v_cvt_pk_bf16_f32 v139, v139, v139
	v_lshlrev_b32_e32 v140, 16, v140
	v_mul_f32_e32 v140, v8, v140
	v_cvt_pk_bf16_f32 v140, v140, v140
	v_lshlrev_b32_e32 v141, 16, v141
	v_mul_f32_e32 v141, v9, v141
	v_cvt_pk_bf16_f32 v141, v141, v141
	v_lshlrev_b32_e32 v142, 16, v142
	v_mul_f32_e32 v142, v10, v142
	v_cvt_pk_bf16_f32 v142, v142, v142
	v_lshlrev_b32_e32 v143, 16, v143
	v_mul_f32_e32 v143, v11, v143
	v_cvt_pk_bf16_f32 v143, v143, v143
	v_lshlrev_b32_e32 v144, 16, v144
	v_mul_f32_e32 v144, v12, v144
	v_cvt_pk_bf16_f32 v144, v144, v144
	v_lshlrev_b32_e32 v145, 16, v145
	v_mul_f32_e32 v145, v13, v145
	v_cvt_pk_bf16_f32 v145, v145, v145
	v_lshlrev_b32_e32 v146, 16, v146
	v_mul_f32_e32 v146, v14, v146
	v_cvt_pk_bf16_f32 v146, v146, v146
	v_lshlrev_b32_e32 v147, 16, v147
	v_mul_f32_e32 v147, v15, v147
	v_cvt_pk_bf16_f32 v147, v147, v147
	s_mov_b64 s[50:51], s[0:1]
	global_store_short v99, v100, s[50:51] offset:64
	s_add_u32 s50, s50, 0x800
	s_addc_u32 s51, s51, 0
	global_store_short v99, v101, s[50:51] offset:64
	s_add_u32 s50, s50, 0x800
	s_addc_u32 s51, s51, 0
	global_store_short v99, v102, s[50:51] offset:64
	s_add_u32 s50, s50, 0x800
	s_addc_u32 s51, s51, 0
	global_store_short v99, v103, s[50:51] offset:64
	s_add_u32 s50, s50, 0x2800
	s_addc_u32 s51, s51, 0
	global_store_short v99, v104, s[50:51] offset:64
	s_add_u32 s50, s50, 0x800
	s_addc_u32 s51, s51, 0
	global_store_short v99, v105, s[50:51] offset:64
	s_add_u32 s50, s50, 0x800
	s_addc_u32 s51, s51, 0
	global_store_short v99, v106, s[50:51] offset:64
	s_add_u32 s50, s50, 0x800
	s_addc_u32 s51, s51, 0
	global_store_short v99, v107, s[50:51] offset:64
	s_add_u32 s50, s50, 0x2800
	s_addc_u32 s51, s51, 0
	global_store_short v99, v108, s[50:51] offset:64
	s_add_u32 s50, s50, 0x800
	s_addc_u32 s51, s51, 0
	global_store_short v99, v109, s[50:51] offset:64
	s_add_u32 s50, s50, 0x800
	s_addc_u32 s51, s51, 0
	global_store_short v99, v110, s[50:51] offset:64
	s_add_u32 s50, s50, 0x800
	s_addc_u32 s51, s51, 0
	global_store_short v99, v111, s[50:51] offset:64
	s_add_u32 s50, s50, 0x2800
	s_addc_u32 s51, s51, 0
	global_store_short v99, v112, s[50:51] offset:64
	s_add_u32 s50, s50, 0x800
	s_addc_u32 s51, s51, 0
	global_store_short v99, v113, s[50:51] offset:64
	s_add_u32 s50, s50, 0x800
	s_addc_u32 s51, s51, 0
	global_store_short v99, v114, s[50:51] offset:64
	s_add_u32 s50, s50, 0x800
	s_addc_u32 s51, s51, 0
	global_store_short v99, v115, s[50:51] offset:64
	s_add_u32 s50, s50, 0x2800
	s_addc_u32 s51, s51, 0
	global_store_short v99, v116, s[50:51] offset:64
	s_add_u32 s50, s50, 0x800
	s_addc_u32 s51, s51, 0
	global_store_short v99, v117, s[50:51] offset:64
	s_add_u32 s50, s50, 0x800
	s_addc_u32 s51, s51, 0
	global_store_short v99, v118, s[50:51] offset:64
	s_add_u32 s50, s50, 0x800
	s_addc_u32 s51, s51, 0
	global_store_short v99, v119, s[50:51] offset:64
	s_add_u32 s50, s50, 0x2800
	s_addc_u32 s51, s51, 0
	global_store_short v99, v120, s[50:51] offset:64
	s_add_u32 s50, s50, 0x800
	s_addc_u32 s51, s51, 0
	global_store_short v99, v121, s[50:51] offset:64
	s_add_u32 s50, s50, 0x800
	s_addc_u32 s51, s51, 0
	global_store_short v99, v122, s[50:51] offset:64
	s_add_u32 s50, s50, 0x800
	s_addc_u32 s51, s51, 0
	global_store_short v99, v123, s[50:51] offset:64
	s_add_u32 s50, s50, 0x2800
	s_addc_u32 s51, s51, 0
	global_store_short v99, v124, s[50:51] offset:64
	s_add_u32 s50, s50, 0x800
	s_addc_u32 s51, s51, 0
	global_store_short v99, v125, s[50:51] offset:64
	s_add_u32 s50, s50, 0x800
	s_addc_u32 s51, s51, 0
	global_store_short v99, v126, s[50:51] offset:64
	s_add_u32 s50, s50, 0x800
	s_addc_u32 s51, s51, 0
	global_store_short v99, v127, s[50:51] offset:64
	s_add_u32 s50, s50, 0x2800
	s_addc_u32 s51, s51, 0
	global_store_short v99, v128, s[50:51] offset:64
	s_add_u32 s50, s50, 0x800
	s_addc_u32 s51, s51, 0
	global_store_short v99, v129, s[50:51] offset:64
	s_add_u32 s50, s50, 0x800
	s_addc_u32 s51, s51, 0
	global_store_short v99, v130, s[50:51] offset:64
	s_add_u32 s50, s50, 0x800
	s_addc_u32 s51, s51, 0
	global_store_short v99, v131, s[50:51] offset:64
	s_add_u32 s50, s50, 0x2800
	s_addc_u32 s51, s51, 0
	global_store_short v99, v132, s[50:51] offset:64
	s_add_u32 s50, s50, 0x800
	s_addc_u32 s51, s51, 0
	global_store_short v99, v133, s[50:51] offset:64
	s_add_u32 s50, s50, 0x800
	s_addc_u32 s51, s51, 0
	global_store_short v99, v134, s[50:51] offset:64
	s_add_u32 s50, s50, 0x800
	s_addc_u32 s51, s51, 0
	global_store_short v99, v135, s[50:51] offset:64
	s_add_u32 s50, s50, 0x2800
	s_addc_u32 s51, s51, 0
	global_store_short v99, v136, s[50:51] offset:64
	s_add_u32 s50, s50, 0x800
	s_addc_u32 s51, s51, 0
	global_store_short v99, v137, s[50:51] offset:64
	s_add_u32 s50, s50, 0x800
	s_addc_u32 s51, s51, 0
	global_store_short v99, v138, s[50:51] offset:64
	s_add_u32 s50, s50, 0x800
	s_addc_u32 s51, s51, 0
	global_store_short v99, v139, s[50:51] offset:64
	s_add_u32 s50, s50, 0x2800
	s_addc_u32 s51, s51, 0
	global_store_short v99, v140, s[50:51] offset:64
	s_add_u32 s50, s50, 0x800
	s_addc_u32 s51, s51, 0
	global_store_short v99, v141, s[50:51] offset:64
	s_add_u32 s50, s50, 0x800
	s_addc_u32 s51, s51, 0
	global_store_short v99, v142, s[50:51] offset:64
	s_add_u32 s50, s50, 0x800
	s_addc_u32 s51, s51, 0
	global_store_short v99, v143, s[50:51] offset:64
	s_add_u32 s50, s50, 0x2800
	s_addc_u32 s51, s51, 0
	global_store_short v99, v144, s[50:51] offset:64
	s_add_u32 s50, s50, 0x800
	s_addc_u32 s51, s51, 0
	global_store_short v99, v145, s[50:51] offset:64
	s_add_u32 s50, s50, 0x800
	s_addc_u32 s51, s51, 0
	global_store_short v99, v146, s[50:51] offset:64
	s_add_u32 s50, s50, 0x800
	s_addc_u32 s51, s51, 0
	global_store_short v99, v147, s[50:51] offset:64
	v_mov_b32_e32 v43, v96
	v_mov_b32_e32 v46, v244
	s_mov_b64 s[50:51], 0x50000
	s_mov_b64 s[52:53], 0x50180
	v_ashrrev_i32_e32 v40, 3, v46
	v_ashrrev_i32_e32 v41, 31, v40
	v_lshlrev_b64 v[0:1], 11, v[40:41]
	v_lshlrev_b32_e32 v4, 4, v46
	v_lshl_add_u64 v[2:3], s[10:11], 0, v[0:1]
	v_and_b32_e32 v42, 0x70, v4
	v_lshl_add_u64 v[180:181], v[2:3], 0, v[42:43]
	v_lshl_add_u64 v[24:25], s[8:9], 0, v[0:1]
	global_load_dwordx4 v[0:3], v[180:181], off
	v_lshl_add_u64 v[8:9], v[180:181], 0, s[40:41]
	global_load_dwordx4 v[4:7], v[8:9], off
	v_lshl_add_u64 v[12:13], v[180:181], 0, s[18:19]
	global_load_dwordx4 v[8:11], v[12:13], off
	v_lshl_add_u64 v[16:17], v[180:181], 0, s[92:93]
	global_load_dwordx4 v[12:15], v[16:17], off
	v_lshl_add_u64 v[20:21], v[180:181], 0, s[62:63]
	global_load_dwordx4 v[16:19], v[20:21], off
	v_lshl_add_u64 v[26:27], v[180:181], 0, s[50:51]
	global_load_dwordx4 v[20:23], v[26:27], off
	v_lshl_add_u64 v[182:183], v[24:25], 0, v[42:43]
	global_load_dwordx4 v[24:27], v[182:183], off
	v_lshl_add_u64 v[32:33], v[182:183], 0, s[40:41]
	global_load_dwordx4 v[28:31], v[32:33], off
	v_lshl_add_u64 v[36:37], v[182:183], 0, s[18:19]
	global_load_dwordx4 v[32:35], v[36:37], off
	v_lshl_add_u64 v[44:45], v[182:183], 0, s[92:93]
	global_load_dwordx4 v[36:39], v[44:45], off
	v_lshl_add_u64 v[44:45], v[180:181], 0, s[94:95]
	global_load_dwordx4 v[98:101], v[44:45], off
	v_lshl_add_u64 v[44:45], v[180:181], 0, s[96:97]
	global_load_dwordx4 v[102:105], v[44:45], off
	v_lshl_add_u64 v[44:45], v[180:181], 0, s[64:65]
	global_load_dwordx4 v[106:109], v[44:45], off
	v_lshl_add_u64 v[44:45], v[180:181], 0, s[66:67]
	global_load_dwordx4 v[110:113], v[44:45], off
	v_lshl_add_u64 v[44:45], v[180:181], 0, s[80:81]
	global_load_dwordx4 v[114:117], v[44:45], off
	s_mov_b64 s[8:9], 0x50080
	v_lshl_add_u64 v[44:45], v[180:181], 0, s[8:9]
	global_load_dwordx4 v[118:121], v[44:45], off
	v_lshl_add_u64 v[44:45], v[182:183], 0, s[94:95]
	global_load_dwordx4 v[122:125], v[44:45], off
	v_lshl_add_u64 v[44:45], v[182:183], 0, s[96:97]
	global_load_dwordx4 v[126:129], v[44:45], off
	v_lshl_add_u64 v[44:45], v[182:183], 0, s[64:65]
	global_load_dwordx4 v[130:133], v[44:45], off
	v_lshl_add_u64 v[44:45], v[182:183], 0, s[66:67]
	global_load_dwordx4 v[134:137], v[44:45], off
	s_waitcnt vmcnt(10)
	v_mul_lo_u32 v40, v40, s85
	v_add_u32_e32 v97, v42, v40
	ds_write_b128 v97, v[0:3]
	ds_write_b128 v97, v[4:7] offset:4608
	ds_write_b128 v97, v[8:11] offset:9216
	ds_write_b128 v97, v[12:15] offset:13824
	ds_write_b128 v97, v[16:19] offset:18432
	ds_write_b128 v97, v[20:23] offset:23040
	ds_write_b128 v97, v[24:27] offset:27648
	ds_write_b128 v97, v[28:31] offset:32256
	ds_write_b128 v97, v[32:35] offset:36864
	ds_write_b128 v97, v[36:39] offset:41472
	v_ashrrev_i32_e32 v0, 7, v46
	v_mul_lo_u32 v0, v0, s45
	v_and_or_b32 v0, v46, 31, v0
	v_lshrrev_b32_e32 v1, 1, v46
	v_and_b32_e32 v2, 0x5f, v46
	v_and_b32_e32 v1, 16, v1
	v_mul_lo_u32 v3, v0, s85
	v_mul_u32_u24_e32 v2, 0x90, v2
	v_mov_b32_e32 v0, 0
	s_mov_b32 s9, 0
	s_movk_i32 s8, 0x80
	v_add_u32_e32 v179, v1, v3
	v_add_u32_e32 v184, v1, v2
	v_mov_b32_e32 v1, v0
	v_mov_b32_e32 v2, v0
	v_mov_b32_e32 v3, v0
	v_mov_b32_e32 v4, v0
	v_mov_b32_e32 v5, v0
	v_mov_b32_e32 v6, v0
	v_mov_b32_e32 v7, v0
	v_mov_b32_e32 v8, v0
	v_mov_b32_e32 v9, v0
	v_mov_b32_e32 v10, v0
	v_mov_b32_e32 v11, v0
	v_mov_b32_e32 v12, v0
	v_mov_b32_e32 v13, v0
	v_mov_b32_e32 v14, v0
	v_mov_b32_e32 v15, v0
	v_mov_b32_e32 v16, v0
	v_mov_b32_e32 v17, v0
	v_mov_b32_e32 v18, v0
	v_mov_b32_e32 v19, v0
	v_mov_b32_e32 v20, v0
	v_mov_b32_e32 v21, v0
	v_mov_b32_e32 v22, v0
	v_mov_b32_e32 v23, v0
	v_mov_b32_e32 v24, v0
	v_mov_b32_e32 v25, v0
	v_mov_b32_e32 v26, v0
	v_mov_b32_e32 v27, v0
	v_mov_b32_e32 v28, v0
	v_mov_b32_e32 v29, v0
	v_mov_b32_e32 v30, v0
	v_mov_b32_e32 v31, v0
	v_mov_b32_e32 v32, v0
	v_mov_b32_e32 v33, v0
	v_mov_b32_e32 v34, v0
	v_mov_b32_e32 v35, v0
	v_mov_b32_e32 v36, v0
	v_mov_b32_e32 v37, v0
	v_mov_b32_e32 v38, v0
	v_mov_b32_e32 v39, v0
	v_mov_b32_e32 v40, v0
	v_mov_b32_e32 v41, v0
	v_mov_b32_e32 v42, v0
	v_mov_b32_e32 v43, v0
	v_mov_b32_e32 v44, v0
	v_mov_b32_e32 v45, v0
	v_mov_b32_e32 v46, v0
	v_mov_b32_e32 v47, v0
	v_mov_b32_e32 v48, v0
	v_mov_b32_e32 v49, v0
	v_mov_b32_e32 v50, v0
	v_mov_b32_e32 v51, v0
	v_mov_b32_e32 v52, v0
	v_mov_b32_e32 v53, v0
	v_mov_b32_e32 v54, v0
	v_mov_b32_e32 v55, v0
	v_mov_b32_e32 v56, v0
	v_mov_b32_e32 v57, v0
	v_mov_b32_e32 v58, v0
	v_mov_b32_e32 v59, v0
	v_mov_b32_e32 v60, v0
	v_mov_b32_e32 v61, v0
	v_mov_b32_e32 v62, v0
	v_mov_b32_e32 v63, v0
	v_mov_b32_e32 v64, v0
	v_mov_b32_e32 v65, v0
	v_mov_b32_e32 v66, v0
	v_mov_b32_e32 v67, v0
	v_mov_b32_e32 v68, v0
	v_mov_b32_e32 v69, v0
	v_mov_b32_e32 v70, v0
	v_mov_b32_e32 v71, v0
	v_mov_b32_e32 v72, v0
	v_mov_b32_e32 v73, v0
	v_mov_b32_e32 v74, v0
	v_mov_b32_e32 v75, v0
	v_mov_b32_e32 v76, v0
	v_mov_b32_e32 v77, v0
	v_mov_b32_e32 v78, v0
	v_mov_b32_e32 v79, v0
	v_mov_b32_e32 v80, v0
	v_mov_b32_e32 v81, v0
	v_mov_b32_e32 v82, v0
	v_mov_b32_e32 v83, v0
	v_mov_b32_e32 v84, v0
	v_mov_b32_e32 v85, v0
	v_mov_b32_e32 v86, v0
	v_mov_b32_e32 v87, v0
	v_mov_b32_e32 v88, v0
	v_mov_b32_e32 v89, v0
	v_mov_b32_e32 v90, v0
	v_mov_b32_e32 v91, v0
	v_mov_b32_e32 v92, v0
	v_mov_b32_e32 v93, v0
	v_mov_b32_e32 v94, v0
	v_mov_b32_e32 v95, v0
	s_waitcnt lgkmcnt(0)
	s_barrier
.LBB0_780:
	s_add_i32 s10, s9, 2
	s_cmp_lt_u32 s9, 14
	s_cselect_b64 s[12:13], -1, 0
	s_and_b64 vcc, s[12:13], exec
	s_cselect_b32 s2, s8, 0x3c0
	s_lshl_b64 s[12:13], s[2:3], 1
	v_lshl_add_u64 v[158:159], v[180:181], 0, s[12:13]
	global_load_dwordx4 v[138:141], v[158:159], off
	v_lshl_add_u64 v[146:147], v[158:159], 0, s[40:41]
	global_load_dwordx4 v[142:145], v[146:147], off
	v_lshl_add_u64 v[150:151], v[158:159], 0, s[18:19]
	global_load_dwordx4 v[146:149], v[150:151], off
	v_lshl_add_u64 v[154:155], v[158:159], 0, s[92:93]
	global_load_dwordx4 v[150:153], v[154:155], off
	v_lshl_add_u64 v[160:161], v[158:159], 0, s[62:63]
	global_load_dwordx4 v[154:157], v[160:161], off
	v_lshl_add_u64 v[162:163], v[158:159], 0, s[50:51]
	global_load_dwordx4 v[158:161], v[162:163], off
	v_lshl_add_u64 v[174:175], v[182:183], 0, s[12:13]
	global_load_dwordx4 v[162:165], v[174:175], off
	v_lshl_add_u64 v[170:171], v[174:175], 0, s[40:41]
	global_load_dwordx4 v[166:169], v[170:171], off
	v_lshl_add_u64 v[176:177], v[174:175], 0, s[18:19]
	global_load_dwordx4 v[170:173], v[176:177], off
	v_lshl_add_u64 v[186:187], v[174:175], 0, s[92:93]
	global_load_dwordx4 v[174:177], v[186:187], off
	ds_read_b128 v[186:189], v179 offset:4608
	ds_read_b128 v[190:193], v179 offset:9216
	ds_read_b128 v[194:197], v184 offset:32256
	ds_read_b128 v[198:201], v179
	ds_read_b128 v[202:205], v179 offset:32
	ds_read_b128 v[206:209], v184 offset:27648
	ds_read_b128 v[210:213], v184 offset:27680
	s_waitcnt lgkmcnt(1)
	v_mfma_f32_32x32x16_bf16 v[80:95], v[198:201], v[206:209], v[80:95]
	s_min_u32 s2, s9, 12
	s_lshl_b32 s2, s2, 7
	s_addk_i32 s8, 0x80
	s_mov_b32 s9, s10
	v_mfma_f32_32x32x16_bf16 v[64:79], v[198:201], v[194:197], v[64:79]
	v_mfma_f32_32x32x16_bf16 v[48:63], v[186:189], v[206:209], v[48:63]
	v_mfma_f32_32x32x16_bf16 v[32:47], v[186:189], v[194:197], v[32:47]
	v_mfma_f32_32x32x16_bf16 v[16:31], v[190:193], v[206:209], v[16:31]
	v_mfma_f32_32x32x16_bf16 v[0:15], v[190:193], v[194:197], v[0:15]
	ds_read_b128 v[186:189], v179 offset:4640
	ds_read_b128 v[190:193], v179 offset:9248
	ds_read_b128 v[194:197], v184 offset:32288
	s_waitcnt lgkmcnt(3)
	v_mfma_f32_32x32x16_bf16 v[80:95], v[202:205], v[210:213], v[80:95]
	s_waitcnt lgkmcnt(0)
	v_mfma_f32_32x32x16_bf16 v[64:79], v[202:205], v[194:197], v[64:79]
	v_mfma_f32_32x32x16_bf16 v[48:63], v[186:189], v[210:213], v[48:63]
	v_mfma_f32_32x32x16_bf16 v[32:47], v[186:189], v[194:197], v[32:47]
	v_mfma_f32_32x32x16_bf16 v[16:31], v[190:193], v[210:213], v[16:31]
	v_mfma_f32_32x32x16_bf16 v[0:15], v[190:193], v[194:197], v[0:15]
	ds_read_b128 v[186:189], v179 offset:64
	ds_read_b128 v[190:193], v179 offset:4672
	ds_read_b128 v[194:197], v179 offset:9280
	ds_read_b128 v[198:201], v184 offset:27712
	ds_read_b128 v[202:205], v184 offset:32320
	s_waitcnt lgkmcnt(1)
	v_mfma_f32_32x32x16_bf16 v[80:95], v[186:189], v[198:201], v[80:95]
	s_waitcnt lgkmcnt(0)
	v_mfma_f32_32x32x16_bf16 v[64:79], v[186:189], v[202:205], v[64:79]
	v_mfma_f32_32x32x16_bf16 v[48:63], v[190:193], v[198:201], v[48:63]
	v_mfma_f32_32x32x16_bf16 v[32:47], v[190:193], v[202:205], v[32:47]
	v_mfma_f32_32x32x16_bf16 v[16:31], v[194:197], v[198:201], v[16:31]
	v_mfma_f32_32x32x16_bf16 v[0:15], v[194:197], v[202:205], v[0:15]
	ds_read_b128 v[186:189], v179 offset:96
	ds_read_b128 v[190:193], v179 offset:4704
	ds_read_b128 v[194:197], v179 offset:9312
	ds_read_b128 v[198:201], v184 offset:27744
	ds_read_b128 v[202:205], v184 offset:32352
	s_waitcnt vmcnt(10)
	s_waitcnt lgkmcnt(0)
	s_barrier
	ds_write_b128 v97, v[98:101]
	ds_write_b128 v97, v[102:105] offset:4608
	ds_write_b128 v97, v[106:109] offset:9216
	ds_write_b128 v97, v[110:113] offset:13824
	ds_write_b128 v97, v[114:117] offset:18432
	ds_write_b128 v97, v[118:121] offset:23040
	ds_write_b128 v97, v[122:125] offset:27648
	ds_write_b128 v97, v[126:129] offset:32256
	ds_write_b128 v97, v[130:133] offset:36864
	ds_write_b128 v97, v[134:137] offset:41472
	v_lshl_add_u64 v[118:119], v[180:181], 0, s[2:3]
	s_waitcnt lgkmcnt(0)
	s_barrier
	v_lshl_add_u64 v[102:103], v[118:119], 0, s[22:23]
	global_load_dwordx4 v[98:101], v[102:103], off
	v_lshl_add_u64 v[106:107], v[118:119], 0, s[76:77]
	global_load_dwordx4 v[102:105], v[106:107], off
	v_lshl_add_u64 v[110:111], v[118:119], 0, s[26:27]
	global_load_dwordx4 v[106:109], v[110:111], off
	v_lshl_add_u64 v[114:115], v[118:119], 0, s[70:71]
	global_load_dwordx4 v[110:113], v[114:115], off
	v_lshl_add_u64 v[120:121], v[118:119], 0, s[48:49]
	global_load_dwordx4 v[114:117], v[120:121], off
	v_lshl_add_u64 v[122:123], v[118:119], 0, s[52:53]
	global_load_dwordx4 v[118:121], v[122:123], off
	v_lshl_add_u64 v[134:135], v[182:183], 0, s[2:3]
	v_mfma_f32_32x32x16_bf16 v[80:95], v[186:189], v[198:201], v[80:95]
	v_lshl_add_u64 v[126:127], v[134:135], 0, s[22:23]
	global_load_dwordx4 v[122:125], v[126:127], off
	v_lshl_add_u64 v[130:131], v[134:135], 0, s[76:77]
	global_load_dwordx4 v[126:129], v[130:131], off
	v_lshl_add_u64 v[136:137], v[134:135], 0, s[26:27]
	global_load_dwordx4 v[130:133], v[136:137], off
	v_mfma_f32_32x32x16_bf16 v[64:79], v[186:189], v[202:205], v[64:79]
	v_lshl_add_u64 v[186:187], v[134:135], 0, s[70:71]
	global_load_dwordx4 v[134:137], v[186:187], off
	v_mfma_f32_32x32x16_bf16 v[48:63], v[190:193], v[198:201], v[48:63]
	v_mfma_f32_32x32x16_bf16 v[32:47], v[190:193], v[202:205], v[32:47]
	v_mfma_f32_32x32x16_bf16 v[16:31], v[194:197], v[198:201], v[16:31]
	v_mfma_f32_32x32x16_bf16 v[0:15], v[194:197], v[202:205], v[0:15]
	ds_read_b128 v[186:189], v179 offset:4608
	ds_read_b128 v[190:193], v179 offset:9216
	ds_read_b128 v[194:197], v184 offset:32256
	ds_read_b128 v[198:201], v179
	ds_read_b128 v[202:205], v179 offset:32
	ds_read_b128 v[206:209], v184 offset:27648
	ds_read_b128 v[210:213], v184 offset:27680
	s_waitcnt lgkmcnt(1)
	v_mfma_f32_32x32x16_bf16 v[80:95], v[198:201], v[206:209], v[80:95]
	v_mfma_f32_32x32x16_bf16 v[64:79], v[198:201], v[194:197], v[64:79]
	v_mfma_f32_32x32x16_bf16 v[48:63], v[186:189], v[206:209], v[48:63]
	v_mfma_f32_32x32x16_bf16 v[32:47], v[186:189], v[194:197], v[32:47]
	v_mfma_f32_32x32x16_bf16 v[16:31], v[190:193], v[206:209], v[16:31]
	v_mfma_f32_32x32x16_bf16 v[0:15], v[190:193], v[194:197], v[0:15]
	ds_read_b128 v[186:189], v179 offset:4640
	ds_read_b128 v[190:193], v179 offset:9248
	ds_read_b128 v[194:197], v184 offset:32288
	s_waitcnt lgkmcnt(3)
	v_mfma_f32_32x32x16_bf16 v[80:95], v[202:205], v[210:213], v[80:95]
	s_waitcnt lgkmcnt(0)
	v_mfma_f32_32x32x16_bf16 v[64:79], v[202:205], v[194:197], v[64:79]
	v_mfma_f32_32x32x16_bf16 v[48:63], v[186:189], v[210:213], v[48:63]
	v_mfma_f32_32x32x16_bf16 v[32:47], v[186:189], v[194:197], v[32:47]
	v_mfma_f32_32x32x16_bf16 v[16:31], v[190:193], v[210:213], v[16:31]
	v_mfma_f32_32x32x16_bf16 v[0:15], v[190:193], v[194:197], v[0:15]
	ds_read_b128 v[186:189], v179 offset:64
	ds_read_b128 v[190:193], v179 offset:4672
	ds_read_b128 v[194:197], v179 offset:9280
	ds_read_b128 v[198:201], v184 offset:27712
	ds_read_b128 v[202:205], v184 offset:32320
	s_waitcnt lgkmcnt(1)
	v_mfma_f32_32x32x16_bf16 v[80:95], v[186:189], v[198:201], v[80:95]
	s_waitcnt lgkmcnt(0)
	v_mfma_f32_32x32x16_bf16 v[64:79], v[186:189], v[202:205], v[64:79]
	v_mfma_f32_32x32x16_bf16 v[48:63], v[190:193], v[198:201], v[48:63]
	v_mfma_f32_32x32x16_bf16 v[32:47], v[190:193], v[202:205], v[32:47]
	v_mfma_f32_32x32x16_bf16 v[16:31], v[194:197], v[198:201], v[16:31]
	v_mfma_f32_32x32x16_bf16 v[0:15], v[194:197], v[202:205], v[0:15]
	ds_read_b128 v[186:189], v179 offset:96
	ds_read_b128 v[190:193], v179 offset:4704
	ds_read_b128 v[194:197], v179 offset:9312
	ds_read_b128 v[198:201], v184 offset:27744
	ds_read_b128 v[202:205], v184 offset:32352
	s_waitcnt vmcnt(10)
	s_waitcnt lgkmcnt(0)
	s_barrier
	ds_write_b128 v97, v[138:141]
	ds_write_b128 v97, v[142:145] offset:4608
	ds_write_b128 v97, v[146:149] offset:9216
	ds_write_b128 v97, v[150:153] offset:13824
	ds_write_b128 v97, v[154:157] offset:18432
	ds_write_b128 v97, v[158:161] offset:23040
	ds_write_b128 v97, v[162:165] offset:27648
	ds_write_b128 v97, v[166:169] offset:32256
	ds_write_b128 v97, v[170:173] offset:36864
	ds_write_b128 v97, v[174:177] offset:41472
	s_waitcnt lgkmcnt(0)
	v_mfma_f32_32x32x16_bf16 v[80:95], v[186:189], v[198:201], v[80:95]
	s_barrier
	v_mfma_f32_32x32x16_bf16 v[64:79], v[186:189], v[202:205], v[64:79]
	v_mfma_f32_32x32x16_bf16 v[48:63], v[190:193], v[198:201], v[48:63]
	v_mfma_f32_32x32x16_bf16 v[32:47], v[190:193], v[202:205], v[32:47]
	v_mfma_f32_32x32x16_bf16 v[16:31], v[194:197], v[198:201], v[16:31]
	v_mfma_f32_32x32x16_bf16 v[0:15], v[194:197], v[202:205], v[0:15]
	s_cbranch_vccnz .LBB0_780
	s_waitcnt vmcnt(0)
	s_lshl_b64 s[4:5], s[4:5], 1
	s_add_u32 s4, s39, s4
	s_addc_u32 s5, s42, s5
	s_add_u32 s4, s4, s6
	s_addc_u32 s5, s5, s7
	v_and_b32_e32 v97, 0x5f, v244
	v_lshrrev_b32_e32 v98, 7, v244
	v_mul_u32_u24_e32 v98, 0x60, v98
	v_lshrrev_b32_e32 v99, 3, v244
	v_and_or_b32 v98, v99, 4, v98
	v_lshl_or_b32 v99, v98, 10, v97
	v_lshlrev_b32_e32 v99, 1, v99
	s_mov_b64 s[12:13], s[0:1]
	global_load_ushort v100, v99, s[12:13]
	s_add_u32 s12, s12, 0x800
	s_addc_u32 s13, s13, 0
	global_load_ushort v101, v99, s[12:13]
	s_add_u32 s12, s12, 0x800
	s_addc_u32 s13, s13, 0
	global_load_ushort v102, v99, s[12:13]
	s_add_u32 s12, s12, 0x800
	s_addc_u32 s13, s13, 0
	global_load_ushort v103, v99, s[12:13]
	s_add_u32 s12, s12, 0x2800
	s_addc_u32 s13, s13, 0
	global_load_ushort v104, v99, s[12:13]
	s_add_u32 s12, s12, 0x800
	s_addc_u32 s13, s13, 0
	global_load_ushort v105, v99, s[12:13]
	s_add_u32 s12, s12, 0x800
	s_addc_u32 s13, s13, 0
	global_load_ushort v106, v99, s[12:13]
	s_add_u32 s12, s12, 0x800
	s_addc_u32 s13, s13, 0
	global_load_ushort v107, v99, s[12:13]
	s_add_u32 s12, s12, 0x2800
	s_addc_u32 s13, s13, 0
	global_load_ushort v108, v99, s[12:13]
	s_add_u32 s12, s12, 0x800
	s_addc_u32 s13, s13, 0
	global_load_ushort v109, v99, s[12:13]
	s_add_u32 s12, s12, 0x800
	s_addc_u32 s13, s13, 0
	global_load_ushort v110, v99, s[12:13]
	s_add_u32 s12, s12, 0x800
	s_addc_u32 s13, s13, 0
	global_load_ushort v111, v99, s[12:13]
	s_add_u32 s12, s12, 0x2800
	s_addc_u32 s13, s13, 0
	global_load_ushort v112, v99, s[12:13]
	s_add_u32 s12, s12, 0x800
	s_addc_u32 s13, s13, 0
	global_load_ushort v113, v99, s[12:13]
	s_add_u32 s12, s12, 0x800
	s_addc_u32 s13, s13, 0
	global_load_ushort v114, v99, s[12:13]
	s_add_u32 s12, s12, 0x800
	s_addc_u32 s13, s13, 0
	global_load_ushort v115, v99, s[12:13]
	s_mov_b64 s[50:51], s[4:5]
	global_load_ushort v116, v99, s[50:51]
	s_add_u32 s50, s50, 0x800
	s_addc_u32 s51, s51, 0
	global_load_ushort v117, v99, s[50:51]
	s_add_u32 s50, s50, 0x800
	s_addc_u32 s51, s51, 0
	global_load_ushort v118, v99, s[50:51]
	s_add_u32 s50, s50, 0x800
	s_addc_u32 s51, s51, 0
	global_load_ushort v119, v99, s[50:51]
	s_add_u32 s50, s50, 0x2800
	s_addc_u32 s51, s51, 0
	global_load_ushort v120, v99, s[50:51]
	s_add_u32 s50, s50, 0x800
	s_addc_u32 s51, s51, 0
	global_load_ushort v121, v99, s[50:51]
	s_add_u32 s50, s50, 0x800
	s_addc_u32 s51, s51, 0
	global_load_ushort v122, v99, s[50:51]
	s_add_u32 s50, s50, 0x800
	s_addc_u32 s51, s51, 0
	global_load_ushort v123, v99, s[50:51]
	s_add_u32 s50, s50, 0x2800
	s_addc_u32 s51, s51, 0
	global_load_ushort v124, v99, s[50:51]
	s_add_u32 s50, s50, 0x800
	s_addc_u32 s51, s51, 0
	global_load_ushort v125, v99, s[50:51]
	s_add_u32 s50, s50, 0x800
	s_addc_u32 s51, s51, 0
	global_load_ushort v126, v99, s[50:51]
	s_add_u32 s50, s50, 0x800
	s_addc_u32 s51, s51, 0
	global_load_ushort v127, v99, s[50:51]
	s_add_u32 s50, s50, 0x2800
	s_addc_u32 s51, s51, 0
	global_load_ushort v128, v99, s[50:51]
	s_add_u32 s50, s50, 0x800
	s_addc_u32 s51, s51, 0
	global_load_ushort v129, v99, s[50:51]
	s_add_u32 s50, s50, 0x800
	s_addc_u32 s51, s51, 0
	global_load_ushort v130, v99, s[50:51]
	s_add_u32 s50, s50, 0x800
	s_addc_u32 s51, s51, 0
	global_load_ushort v131, v99, s[50:51]
	s_waitcnt vmcnt(0)
	v_lshlrev_b32_e32 v100, 16, v100
	v_lshlrev_b32_e32 v116, 16, v116
	v_fmac_f32_e32 v100, v80, v116
	v_cvt_pk_bf16_f32 v100, v100, v100
	v_lshlrev_b32_e32 v101, 16, v101
	v_lshlrev_b32_e32 v117, 16, v117
	v_fmac_f32_e32 v101, v81, v117
	v_cvt_pk_bf16_f32 v101, v101, v101
	v_lshlrev_b32_e32 v102, 16, v102
	v_lshlrev_b32_e32 v118, 16, v118
	v_fmac_f32_e32 v102, v82, v118
	v_cvt_pk_bf16_f32 v102, v102, v102
	v_lshlrev_b32_e32 v103, 16, v103
	v_lshlrev_b32_e32 v119, 16, v119
	v_fmac_f32_e32 v103, v83, v119
	v_cvt_pk_bf16_f32 v103, v103, v103
	v_lshlrev_b32_e32 v104, 16, v104
	v_lshlrev_b32_e32 v120, 16, v120
	v_fmac_f32_e32 v104, v84, v120
	v_cvt_pk_bf16_f32 v104, v104, v104
	v_lshlrev_b32_e32 v105, 16, v105
	v_lshlrev_b32_e32 v121, 16, v121
	v_fmac_f32_e32 v105, v85, v121
	v_cvt_pk_bf16_f32 v105, v105, v105
	v_lshlrev_b32_e32 v106, 16, v106
	v_lshlrev_b32_e32 v122, 16, v122
	v_fmac_f32_e32 v106, v86, v122
	v_cvt_pk_bf16_f32 v106, v106, v106
	v_lshlrev_b32_e32 v107, 16, v107
	v_lshlrev_b32_e32 v123, 16, v123
	v_fmac_f32_e32 v107, v87, v123
	v_cvt_pk_bf16_f32 v107, v107, v107
	v_lshlrev_b32_e32 v108, 16, v108
	v_lshlrev_b32_e32 v124, 16, v124
	v_fmac_f32_e32 v108, v88, v124
	v_cvt_pk_bf16_f32 v108, v108, v108
	v_lshlrev_b32_e32 v109, 16, v109
	v_lshlrev_b32_e32 v125, 16, v125
	v_fmac_f32_e32 v109, v89, v125
	v_cvt_pk_bf16_f32 v109, v109, v109
	v_lshlrev_b32_e32 v110, 16, v110
	v_lshlrev_b32_e32 v126, 16, v126
	v_fmac_f32_e32 v110, v90, v126
	v_cvt_pk_bf16_f32 v110, v110, v110
	v_lshlrev_b32_e32 v111, 16, v111
	v_lshlrev_b32_e32 v127, 16, v127
	v_fmac_f32_e32 v111, v91, v127
	v_cvt_pk_bf16_f32 v111, v111, v111
	v_lshlrev_b32_e32 v112, 16, v112
	v_lshlrev_b32_e32 v128, 16, v128
	v_fmac_f32_e32 v112, v92, v128
	v_cvt_pk_bf16_f32 v112, v112, v112
	v_lshlrev_b32_e32 v113, 16, v113
	v_lshlrev_b32_e32 v129, 16, v129
	v_fmac_f32_e32 v113, v93, v129
	v_cvt_pk_bf16_f32 v113, v113, v113
	v_lshlrev_b32_e32 v114, 16, v114
	v_lshlrev_b32_e32 v130, 16, v130
	v_fmac_f32_e32 v114, v94, v130
	v_cvt_pk_bf16_f32 v114, v114, v114
	v_lshlrev_b32_e32 v115, 16, v115
	v_lshlrev_b32_e32 v131, 16, v131
	v_fmac_f32_e32 v115, v95, v131
	v_cvt_pk_bf16_f32 v115, v115, v115
	s_mov_b64 s[52:53], s[0:1]
	global_store_short v99, v100, s[52:53]
	s_add_u32 s52, s52, 0x800
	s_addc_u32 s53, s53, 0
	global_store_short v99, v101, s[52:53]
	s_add_u32 s52, s52, 0x800
	s_addc_u32 s53, s53, 0
	global_store_short v99, v102, s[52:53]
	s_add_u32 s52, s52, 0x800
	s_addc_u32 s53, s53, 0
	global_store_short v99, v103, s[52:53]
	s_add_u32 s52, s52, 0x2800
	s_addc_u32 s53, s53, 0
	global_store_short v99, v104, s[52:53]
	s_add_u32 s52, s52, 0x800
	s_addc_u32 s53, s53, 0
	global_store_short v99, v105, s[52:53]
	s_add_u32 s52, s52, 0x800
	s_addc_u32 s53, s53, 0
	global_store_short v99, v106, s[52:53]
	s_add_u32 s52, s52, 0x800
	s_addc_u32 s53, s53, 0
	global_store_short v99, v107, s[52:53]
	s_add_u32 s52, s52, 0x2800
	s_addc_u32 s53, s53, 0
	global_store_short v99, v108, s[52:53]
	s_add_u32 s52, s52, 0x800
	s_addc_u32 s53, s53, 0
	global_store_short v99, v109, s[52:53]
	s_add_u32 s52, s52, 0x800
	s_addc_u32 s53, s53, 0
	global_store_short v99, v110, s[52:53]
	s_add_u32 s52, s52, 0x800
	s_addc_u32 s53, s53, 0
	global_store_short v99, v111, s[52:53]
	s_add_u32 s52, s52, 0x2800
	s_addc_u32 s53, s53, 0
	global_store_short v99, v112, s[52:53]
	s_add_u32 s52, s52, 0x800
	s_addc_u32 s53, s53, 0
	global_store_short v99, v113, s[52:53]
	s_add_u32 s52, s52, 0x800
	s_addc_u32 s53, s53, 0
	global_store_short v99, v114, s[52:53]
	s_add_u32 s52, s52, 0x800
	s_addc_u32 s53, s53, 0
	global_store_short v99, v115, s[52:53]
	s_mov_b64 s[12:13], s[0:1]
	s_add_u32 s12, s12, 0x10000
	s_addc_u32 s13, s13, 0
	global_load_ushort v100, v99, s[12:13]
	s_add_u32 s12, s12, 0x800
	s_addc_u32 s13, s13, 0
	global_load_ushort v101, v99, s[12:13]
	s_add_u32 s12, s12, 0x800
	s_addc_u32 s13, s13, 0
	global_load_ushort v102, v99, s[12:13]
	s_add_u32 s12, s12, 0x800
	s_addc_u32 s13, s13, 0
	global_load_ushort v103, v99, s[12:13]
	s_add_u32 s12, s12, 0x2800
	s_addc_u32 s13, s13, 0
	global_load_ushort v104, v99, s[12:13]
	s_add_u32 s12, s12, 0x800
	s_addc_u32 s13, s13, 0
	global_load_ushort v105, v99, s[12:13]
	s_add_u32 s12, s12, 0x800
	s_addc_u32 s13, s13, 0
	global_load_ushort v106, v99, s[12:13]
	s_add_u32 s12, s12, 0x800
	s_addc_u32 s13, s13, 0
	global_load_ushort v107, v99, s[12:13]
	s_add_u32 s12, s12, 0x2800
	s_addc_u32 s13, s13, 0
	global_load_ushort v108, v99, s[12:13]
	s_add_u32 s12, s12, 0x800
	s_addc_u32 s13, s13, 0
	global_load_ushort v109, v99, s[12:13]
	s_add_u32 s12, s12, 0x800
	s_addc_u32 s13, s13, 0
	global_load_ushort v110, v99, s[12:13]
	s_add_u32 s12, s12, 0x800
	s_addc_u32 s13, s13, 0
	global_load_ushort v111, v99, s[12:13]
	s_add_u32 s12, s12, 0x2800
	s_addc_u32 s13, s13, 0
	global_load_ushort v112, v99, s[12:13]
	s_add_u32 s12, s12, 0x800
	s_addc_u32 s13, s13, 0
	global_load_ushort v113, v99, s[12:13]
	s_add_u32 s12, s12, 0x800
	s_addc_u32 s13, s13, 0
	global_load_ushort v114, v99, s[12:13]
	s_add_u32 s12, s12, 0x800
	s_addc_u32 s13, s13, 0
	global_load_ushort v115, v99, s[12:13]
	s_mov_b64 s[50:51], s[4:5]
	s_add_u32 s50, s50, 0x10000
	s_addc_u32 s51, s51, 0
	global_load_ushort v116, v99, s[50:51]
	s_add_u32 s50, s50, 0x800
	s_addc_u32 s51, s51, 0
	global_load_ushort v117, v99, s[50:51]
	s_add_u32 s50, s50, 0x800
	s_addc_u32 s51, s51, 0
	global_load_ushort v118, v99, s[50:51]
	s_add_u32 s50, s50, 0x800
	s_addc_u32 s51, s51, 0
	global_load_ushort v119, v99, s[50:51]
	s_add_u32 s50, s50, 0x2800
	s_addc_u32 s51, s51, 0
	global_load_ushort v120, v99, s[50:51]
	s_add_u32 s50, s50, 0x800
	s_addc_u32 s51, s51, 0
	global_load_ushort v121, v99, s[50:51]
	s_add_u32 s50, s50, 0x800
	s_addc_u32 s51, s51, 0
	global_load_ushort v122, v99, s[50:51]
	s_add_u32 s50, s50, 0x800
	s_addc_u32 s51, s51, 0
	global_load_ushort v123, v99, s[50:51]
	s_add_u32 s50, s50, 0x2800
	s_addc_u32 s51, s51, 0
	global_load_ushort v124, v99, s[50:51]
	s_add_u32 s50, s50, 0x800
	s_addc_u32 s51, s51, 0
	global_load_ushort v125, v99, s[50:51]
	s_add_u32 s50, s50, 0x800
	s_addc_u32 s51, s51, 0
	global_load_ushort v126, v99, s[50:51]
	s_add_u32 s50, s50, 0x800
	s_addc_u32 s51, s51, 0
	global_load_ushort v127, v99, s[50:51]
	s_add_u32 s50, s50, 0x2800
	s_addc_u32 s51, s51, 0
	global_load_ushort v128, v99, s[50:51]
	s_add_u32 s50, s50, 0x800
	s_addc_u32 s51, s51, 0
	global_load_ushort v129, v99, s[50:51]
	s_add_u32 s50, s50, 0x800
	s_addc_u32 s51, s51, 0
	global_load_ushort v130, v99, s[50:51]
	s_add_u32 s50, s50, 0x800
	s_addc_u32 s51, s51, 0
	global_load_ushort v131, v99, s[50:51]
	s_waitcnt vmcnt(0)
	v_lshlrev_b32_e32 v100, 16, v100
	v_lshlrev_b32_e32 v116, 16, v116
	v_fmac_f32_e32 v100, v48, v116
	v_cvt_pk_bf16_f32 v100, v100, v100
	v_lshlrev_b32_e32 v101, 16, v101
	v_lshlrev_b32_e32 v117, 16, v117
	v_fmac_f32_e32 v101, v49, v117
	v_cvt_pk_bf16_f32 v101, v101, v101
	v_lshlrev_b32_e32 v102, 16, v102
	v_lshlrev_b32_e32 v118, 16, v118
	v_fmac_f32_e32 v102, v50, v118
	v_cvt_pk_bf16_f32 v102, v102, v102
	v_lshlrev_b32_e32 v103, 16, v103
	v_lshlrev_b32_e32 v119, 16, v119
	v_fmac_f32_e32 v103, v51, v119
	v_cvt_pk_bf16_f32 v103, v103, v103
	v_lshlrev_b32_e32 v104, 16, v104
	v_lshlrev_b32_e32 v120, 16, v120
	v_fmac_f32_e32 v104, v52, v120
	v_cvt_pk_bf16_f32 v104, v104, v104
	v_lshlrev_b32_e32 v105, 16, v105
	v_lshlrev_b32_e32 v121, 16, v121
	v_fmac_f32_e32 v105, v53, v121
	v_cvt_pk_bf16_f32 v105, v105, v105
	v_lshlrev_b32_e32 v106, 16, v106
	v_lshlrev_b32_e32 v122, 16, v122
	v_fmac_f32_e32 v106, v54, v122
	v_cvt_pk_bf16_f32 v106, v106, v106
	v_lshlrev_b32_e32 v107, 16, v107
	v_lshlrev_b32_e32 v123, 16, v123
	v_fmac_f32_e32 v107, v55, v123
	v_cvt_pk_bf16_f32 v107, v107, v107
	v_lshlrev_b32_e32 v108, 16, v108
	v_lshlrev_b32_e32 v124, 16, v124
	v_fmac_f32_e32 v108, v56, v124
	v_cvt_pk_bf16_f32 v108, v108, v108
	v_lshlrev_b32_e32 v109, 16, v109
	v_lshlrev_b32_e32 v125, 16, v125
	v_fmac_f32_e32 v109, v57, v125
	v_cvt_pk_bf16_f32 v109, v109, v109
	v_lshlrev_b32_e32 v110, 16, v110
	v_lshlrev_b32_e32 v126, 16, v126
	v_fmac_f32_e32 v110, v58, v126
	v_cvt_pk_bf16_f32 v110, v110, v110
	v_lshlrev_b32_e32 v111, 16, v111
	v_lshlrev_b32_e32 v127, 16, v127
	v_fmac_f32_e32 v111, v59, v127
	v_cvt_pk_bf16_f32 v111, v111, v111
	v_lshlrev_b32_e32 v112, 16, v112
	v_lshlrev_b32_e32 v128, 16, v128
	v_fmac_f32_e32 v112, v60, v128
	v_cvt_pk_bf16_f32 v112, v112, v112
	v_lshlrev_b32_e32 v113, 16, v113
	v_lshlrev_b32_e32 v129, 16, v129
	v_fmac_f32_e32 v113, v61, v129
	v_cvt_pk_bf16_f32 v113, v113, v113
	v_lshlrev_b32_e32 v114, 16, v114
	v_lshlrev_b32_e32 v130, 16, v130
	v_fmac_f32_e32 v114, v62, v130
	v_cvt_pk_bf16_f32 v114, v114, v114
	v_lshlrev_b32_e32 v115, 16, v115
	v_lshlrev_b32_e32 v131, 16, v131
	v_fmac_f32_e32 v115, v63, v131
	v_cvt_pk_bf16_f32 v115, v115, v115
	s_mov_b64 s[52:53], s[0:1]
	s_add_u32 s52, s52, 0x10000
	s_addc_u32 s53, s53, 0
	global_store_short v99, v100, s[52:53]
	s_add_u32 s52, s52, 0x800
	s_addc_u32 s53, s53, 0
	global_store_short v99, v101, s[52:53]
	s_add_u32 s52, s52, 0x800
	s_addc_u32 s53, s53, 0
	global_store_short v99, v102, s[52:53]
	s_add_u32 s52, s52, 0x800
	s_addc_u32 s53, s53, 0
	global_store_short v99, v103, s[52:53]
	s_add_u32 s52, s52, 0x2800
	s_addc_u32 s53, s53, 0
	global_store_short v99, v104, s[52:53]
	s_add_u32 s52, s52, 0x800
	s_addc_u32 s53, s53, 0
	global_store_short v99, v105, s[52:53]
	s_add_u32 s52, s52, 0x800
	s_addc_u32 s53, s53, 0
	global_store_short v99, v106, s[52:53]
	s_add_u32 s52, s52, 0x800
	s_addc_u32 s53, s53, 0
	global_store_short v99, v107, s[52:53]
	s_add_u32 s52, s52, 0x2800
	s_addc_u32 s53, s53, 0
	global_store_short v99, v108, s[52:53]
	s_add_u32 s52, s52, 0x800
	s_addc_u32 s53, s53, 0
	global_store_short v99, v109, s[52:53]
	s_add_u32 s52, s52, 0x800
	s_addc_u32 s53, s53, 0
	global_store_short v99, v110, s[52:53]
	s_add_u32 s52, s52, 0x800
	s_addc_u32 s53, s53, 0
	global_store_short v99, v111, s[52:53]
	s_add_u32 s52, s52, 0x2800
	s_addc_u32 s53, s53, 0
	global_store_short v99, v112, s[52:53]
	s_add_u32 s52, s52, 0x800
	s_addc_u32 s53, s53, 0
	global_store_short v99, v113, s[52:53]
	s_add_u32 s52, s52, 0x800
	s_addc_u32 s53, s53, 0
	global_store_short v99, v114, s[52:53]
	s_add_u32 s52, s52, 0x800
	s_addc_u32 s53, s53, 0
	global_store_short v99, v115, s[52:53]
	s_mov_b64 s[12:13], s[0:1]
	s_add_u32 s12, s12, 0x20000
	s_addc_u32 s13, s13, 0
	global_load_ushort v100, v99, s[12:13]
	s_add_u32 s12, s12, 0x800
	s_addc_u32 s13, s13, 0
	global_load_ushort v101, v99, s[12:13]
	s_add_u32 s12, s12, 0x800
	s_addc_u32 s13, s13, 0
	global_load_ushort v102, v99, s[12:13]
	s_add_u32 s12, s12, 0x800
	s_addc_u32 s13, s13, 0
	global_load_ushort v103, v99, s[12:13]
	s_add_u32 s12, s12, 0x2800
	s_addc_u32 s13, s13, 0
	global_load_ushort v104, v99, s[12:13]
	s_add_u32 s12, s12, 0x800
	s_addc_u32 s13, s13, 0
	global_load_ushort v105, v99, s[12:13]
	s_add_u32 s12, s12, 0x800
	s_addc_u32 s13, s13, 0
	global_load_ushort v106, v99, s[12:13]
	s_add_u32 s12, s12, 0x800
	s_addc_u32 s13, s13, 0
	global_load_ushort v107, v99, s[12:13]
	s_add_u32 s12, s12, 0x2800
	s_addc_u32 s13, s13, 0
	global_load_ushort v108, v99, s[12:13]
	s_add_u32 s12, s12, 0x800
	s_addc_u32 s13, s13, 0
	global_load_ushort v109, v99, s[12:13]
	s_add_u32 s12, s12, 0x800
	s_addc_u32 s13, s13, 0
	global_load_ushort v110, v99, s[12:13]
	s_add_u32 s12, s12, 0x800
	s_addc_u32 s13, s13, 0
	global_load_ushort v111, v99, s[12:13]
	s_add_u32 s12, s12, 0x2800
	s_addc_u32 s13, s13, 0
	global_load_ushort v112, v99, s[12:13]
	s_add_u32 s12, s12, 0x800
	s_addc_u32 s13, s13, 0
	global_load_ushort v113, v99, s[12:13]
	s_add_u32 s12, s12, 0x800
	s_addc_u32 s13, s13, 0
	global_load_ushort v114, v99, s[12:13]
	s_add_u32 s12, s12, 0x800
	s_addc_u32 s13, s13, 0
	global_load_ushort v115, v99, s[12:13]
	s_mov_b64 s[50:51], s[4:5]
	s_add_u32 s50, s50, 0x20000
	s_addc_u32 s51, s51, 0
	global_load_ushort v116, v99, s[50:51]
	s_add_u32 s50, s50, 0x800
	s_addc_u32 s51, s51, 0
	global_load_ushort v117, v99, s[50:51]
	s_add_u32 s50, s50, 0x800
	s_addc_u32 s51, s51, 0
	global_load_ushort v118, v99, s[50:51]
	s_add_u32 s50, s50, 0x800
	s_addc_u32 s51, s51, 0
	global_load_ushort v119, v99, s[50:51]
	s_add_u32 s50, s50, 0x2800
	s_addc_u32 s51, s51, 0
	global_load_ushort v120, v99, s[50:51]
	s_add_u32 s50, s50, 0x800
	s_addc_u32 s51, s51, 0
	global_load_ushort v121, v99, s[50:51]
	s_add_u32 s50, s50, 0x800
	s_addc_u32 s51, s51, 0
	global_load_ushort v122, v99, s[50:51]
	s_add_u32 s50, s50, 0x800
	s_addc_u32 s51, s51, 0
	global_load_ushort v123, v99, s[50:51]
	s_add_u32 s50, s50, 0x2800
	s_addc_u32 s51, s51, 0
	global_load_ushort v124, v99, s[50:51]
	s_add_u32 s50, s50, 0x800
	s_addc_u32 s51, s51, 0
	global_load_ushort v125, v99, s[50:51]
	s_add_u32 s50, s50, 0x800
	s_addc_u32 s51, s51, 0
	global_load_ushort v126, v99, s[50:51]
	s_add_u32 s50, s50, 0x800
	s_addc_u32 s51, s51, 0
	global_load_ushort v127, v99, s[50:51]
	s_add_u32 s50, s50, 0x2800
	s_addc_u32 s51, s51, 0
	global_load_ushort v128, v99, s[50:51]
	s_add_u32 s50, s50, 0x800
	s_addc_u32 s51, s51, 0
	global_load_ushort v129, v99, s[50:51]
	s_add_u32 s50, s50, 0x800
	s_addc_u32 s51, s51, 0
	global_load_ushort v130, v99, s[50:51]
	s_add_u32 s50, s50, 0x800
	s_addc_u32 s51, s51, 0
	global_load_ushort v131, v99, s[50:51]
	s_waitcnt vmcnt(0)
	v_lshlrev_b32_e32 v100, 16, v100
	v_lshlrev_b32_e32 v116, 16, v116
	v_fmac_f32_e32 v100, v16, v116
	v_cvt_pk_bf16_f32 v100, v100, v100
	v_lshlrev_b32_e32 v101, 16, v101
	v_lshlrev_b32_e32 v117, 16, v117
	v_fmac_f32_e32 v101, v17, v117
	v_cvt_pk_bf16_f32 v101, v101, v101
	v_lshlrev_b32_e32 v102, 16, v102
	v_lshlrev_b32_e32 v118, 16, v118
	v_fmac_f32_e32 v102, v18, v118
	v_cvt_pk_bf16_f32 v102, v102, v102
	v_lshlrev_b32_e32 v103, 16, v103
	v_lshlrev_b32_e32 v119, 16, v119
	v_fmac_f32_e32 v103, v19, v119
	v_cvt_pk_bf16_f32 v103, v103, v103
	v_lshlrev_b32_e32 v104, 16, v104
	v_lshlrev_b32_e32 v120, 16, v120
	v_fmac_f32_e32 v104, v20, v120
	v_cvt_pk_bf16_f32 v104, v104, v104
	v_lshlrev_b32_e32 v105, 16, v105
	v_lshlrev_b32_e32 v121, 16, v121
	v_fmac_f32_e32 v105, v21, v121
	v_cvt_pk_bf16_f32 v105, v105, v105
	v_lshlrev_b32_e32 v106, 16, v106
	v_lshlrev_b32_e32 v122, 16, v122
	v_fmac_f32_e32 v106, v22, v122
	v_cvt_pk_bf16_f32 v106, v106, v106
	v_lshlrev_b32_e32 v107, 16, v107
	v_lshlrev_b32_e32 v123, 16, v123
	v_fmac_f32_e32 v107, v23, v123
	v_cvt_pk_bf16_f32 v107, v107, v107
	v_lshlrev_b32_e32 v108, 16, v108
	v_lshlrev_b32_e32 v124, 16, v124
	v_fmac_f32_e32 v108, v24, v124
	v_cvt_pk_bf16_f32 v108, v108, v108
	v_lshlrev_b32_e32 v109, 16, v109
	v_lshlrev_b32_e32 v125, 16, v125
	v_fmac_f32_e32 v109, v25, v125
	v_cvt_pk_bf16_f32 v109, v109, v109
	v_lshlrev_b32_e32 v110, 16, v110
	v_lshlrev_b32_e32 v126, 16, v126
	v_fmac_f32_e32 v110, v26, v126
	v_cvt_pk_bf16_f32 v110, v110, v110
	v_lshlrev_b32_e32 v111, 16, v111
	v_lshlrev_b32_e32 v127, 16, v127
	v_fmac_f32_e32 v111, v27, v127
	v_cvt_pk_bf16_f32 v111, v111, v111
	v_lshlrev_b32_e32 v112, 16, v112
	v_lshlrev_b32_e32 v128, 16, v128
	v_fmac_f32_e32 v112, v28, v128
	v_cvt_pk_bf16_f32 v112, v112, v112
	v_lshlrev_b32_e32 v113, 16, v113
	v_lshlrev_b32_e32 v129, 16, v129
	v_fmac_f32_e32 v113, v29, v129
	v_cvt_pk_bf16_f32 v113, v113, v113
	v_lshlrev_b32_e32 v114, 16, v114
	v_lshlrev_b32_e32 v130, 16, v130
	v_fmac_f32_e32 v114, v30, v130
	v_cvt_pk_bf16_f32 v114, v114, v114
	v_lshlrev_b32_e32 v115, 16, v115
	v_lshlrev_b32_e32 v131, 16, v131
	v_fmac_f32_e32 v115, v31, v131
	v_cvt_pk_bf16_f32 v115, v115, v115
	s_mov_b64 s[52:53], s[0:1]
	s_add_u32 s52, s52, 0x20000
	s_addc_u32 s53, s53, 0
	global_store_short v99, v100, s[52:53]
	s_add_u32 s52, s52, 0x800
	s_addc_u32 s53, s53, 0
	global_store_short v99, v101, s[52:53]
	s_add_u32 s52, s52, 0x800
	s_addc_u32 s53, s53, 0
	global_store_short v99, v102, s[52:53]
	s_add_u32 s52, s52, 0x800
	s_addc_u32 s53, s53, 0
	global_store_short v99, v103, s[52:53]
	s_add_u32 s52, s52, 0x2800
	s_addc_u32 s53, s53, 0
	global_store_short v99, v104, s[52:53]
	s_add_u32 s52, s52, 0x800
	s_addc_u32 s53, s53, 0
	global_store_short v99, v105, s[52:53]
	s_add_u32 s52, s52, 0x800
	s_addc_u32 s53, s53, 0
	global_store_short v99, v106, s[52:53]
	s_add_u32 s52, s52, 0x800
	s_addc_u32 s53, s53, 0
	global_store_short v99, v107, s[52:53]
	s_add_u32 s52, s52, 0x2800
	s_addc_u32 s53, s53, 0
	global_store_short v99, v108, s[52:53]
	s_add_u32 s52, s52, 0x800
	s_addc_u32 s53, s53, 0
	global_store_short v99, v109, s[52:53]
	s_add_u32 s52, s52, 0x800
	s_addc_u32 s53, s53, 0
	global_store_short v99, v110, s[52:53]
	s_add_u32 s52, s52, 0x800
	s_addc_u32 s53, s53, 0
	global_store_short v99, v111, s[52:53]
	s_add_u32 s52, s52, 0x2800
	s_addc_u32 s53, s53, 0
	global_store_short v99, v112, s[52:53]
	s_add_u32 s52, s52, 0x800
	s_addc_u32 s53, s53, 0
	global_store_short v99, v113, s[52:53]
	s_add_u32 s52, s52, 0x800
	s_addc_u32 s53, s53, 0
	global_store_short v99, v114, s[52:53]
	s_add_u32 s52, s52, 0x800
	s_addc_u32 s53, s53, 0
	global_store_short v99, v115, s[52:53]
	s_mov_b64 s[12:13], s[0:1]
	global_load_ushort v100, v99, s[12:13] offset:64
	s_add_u32 s12, s12, 0x800
	s_addc_u32 s13, s13, 0
	global_load_ushort v101, v99, s[12:13] offset:64
	s_add_u32 s12, s12, 0x800
	s_addc_u32 s13, s13, 0
	global_load_ushort v102, v99, s[12:13] offset:64
	s_add_u32 s12, s12, 0x800
	s_addc_u32 s13, s13, 0
	global_load_ushort v103, v99, s[12:13] offset:64
	s_add_u32 s12, s12, 0x2800
	s_addc_u32 s13, s13, 0
	global_load_ushort v104, v99, s[12:13] offset:64
	s_add_u32 s12, s12, 0x800
	s_addc_u32 s13, s13, 0
	global_load_ushort v105, v99, s[12:13] offset:64
	s_add_u32 s12, s12, 0x800
	s_addc_u32 s13, s13, 0
	global_load_ushort v106, v99, s[12:13] offset:64
	s_add_u32 s12, s12, 0x800
	s_addc_u32 s13, s13, 0
	global_load_ushort v107, v99, s[12:13] offset:64
	s_add_u32 s12, s12, 0x2800
	s_addc_u32 s13, s13, 0
	global_load_ushort v108, v99, s[12:13] offset:64
	s_add_u32 s12, s12, 0x800
	s_addc_u32 s13, s13, 0
	global_load_ushort v109, v99, s[12:13] offset:64
	s_add_u32 s12, s12, 0x800
	s_addc_u32 s13, s13, 0
	global_load_ushort v110, v99, s[12:13] offset:64
	s_add_u32 s12, s12, 0x800
	s_addc_u32 s13, s13, 0
	global_load_ushort v111, v99, s[12:13] offset:64
	s_add_u32 s12, s12, 0x2800
	s_addc_u32 s13, s13, 0
	global_load_ushort v112, v99, s[12:13] offset:64
	s_add_u32 s12, s12, 0x800
	s_addc_u32 s13, s13, 0
	global_load_ushort v113, v99, s[12:13] offset:64
	s_add_u32 s12, s12, 0x800
	s_addc_u32 s13, s13, 0
	global_load_ushort v114, v99, s[12:13] offset:64
	s_add_u32 s12, s12, 0x800
	s_addc_u32 s13, s13, 0
	global_load_ushort v115, v99, s[12:13] offset:64
	s_mov_b64 s[50:51], s[4:5]
	global_load_ushort v116, v99, s[50:51] offset:64
	s_add_u32 s50, s50, 0x800
	s_addc_u32 s51, s51, 0
	global_load_ushort v117, v99, s[50:51] offset:64
	s_add_u32 s50, s50, 0x800
	s_addc_u32 s51, s51, 0
	global_load_ushort v118, v99, s[50:51] offset:64
	s_add_u32 s50, s50, 0x800
	s_addc_u32 s51, s51, 0
	global_load_ushort v119, v99, s[50:51] offset:64
	s_add_u32 s50, s50, 0x2800
	s_addc_u32 s51, s51, 0
	global_load_ushort v120, v99, s[50:51] offset:64
	s_add_u32 s50, s50, 0x800
	s_addc_u32 s51, s51, 0
	global_load_ushort v121, v99, s[50:51] offset:64
	s_add_u32 s50, s50, 0x800
	s_addc_u32 s51, s51, 0
	global_load_ushort v122, v99, s[50:51] offset:64
	s_add_u32 s50, s50, 0x800
	s_addc_u32 s51, s51, 0
	global_load_ushort v123, v99, s[50:51] offset:64
	s_add_u32 s50, s50, 0x2800
	s_addc_u32 s51, s51, 0
	global_load_ushort v124, v99, s[50:51] offset:64
	s_add_u32 s50, s50, 0x800
	s_addc_u32 s51, s51, 0
	global_load_ushort v125, v99, s[50:51] offset:64
	s_add_u32 s50, s50, 0x800
	s_addc_u32 s51, s51, 0
	global_load_ushort v126, v99, s[50:51] offset:64
	s_add_u32 s50, s50, 0x800
	s_addc_u32 s51, s51, 0
	global_load_ushort v127, v99, s[50:51] offset:64
	s_add_u32 s50, s50, 0x2800
	s_addc_u32 s51, s51, 0
	global_load_ushort v128, v99, s[50:51] offset:64
	s_add_u32 s50, s50, 0x800
	s_addc_u32 s51, s51, 0
	global_load_ushort v129, v99, s[50:51] offset:64
	s_add_u32 s50, s50, 0x800
	s_addc_u32 s51, s51, 0
	global_load_ushort v130, v99, s[50:51] offset:64
	s_add_u32 s50, s50, 0x800
	s_addc_u32 s51, s51, 0
	global_load_ushort v131, v99, s[50:51] offset:64
	s_waitcnt vmcnt(0)
	v_lshlrev_b32_e32 v100, 16, v100
	v_lshlrev_b32_e32 v116, 16, v116
	v_fmac_f32_e32 v100, v64, v116
	v_cvt_pk_bf16_f32 v100, v100, v100
	v_lshlrev_b32_e32 v101, 16, v101
	v_lshlrev_b32_e32 v117, 16, v117
	v_fmac_f32_e32 v101, v65, v117
	v_cvt_pk_bf16_f32 v101, v101, v101
	v_lshlrev_b32_e32 v102, 16, v102
	v_lshlrev_b32_e32 v118, 16, v118
	v_fmac_f32_e32 v102, v66, v118
	v_cvt_pk_bf16_f32 v102, v102, v102
	v_lshlrev_b32_e32 v103, 16, v103
	v_lshlrev_b32_e32 v119, 16, v119
	v_fmac_f32_e32 v103, v67, v119
	v_cvt_pk_bf16_f32 v103, v103, v103
	v_lshlrev_b32_e32 v104, 16, v104
	v_lshlrev_b32_e32 v120, 16, v120
	v_fmac_f32_e32 v104, v68, v120
	v_cvt_pk_bf16_f32 v104, v104, v104
	v_lshlrev_b32_e32 v105, 16, v105
	v_lshlrev_b32_e32 v121, 16, v121
	v_fmac_f32_e32 v105, v69, v121
	v_cvt_pk_bf16_f32 v105, v105, v105
	v_lshlrev_b32_e32 v106, 16, v106
	v_lshlrev_b32_e32 v122, 16, v122
	v_fmac_f32_e32 v106, v70, v122
	v_cvt_pk_bf16_f32 v106, v106, v106
	v_lshlrev_b32_e32 v107, 16, v107
	v_lshlrev_b32_e32 v123, 16, v123
	v_fmac_f32_e32 v107, v71, v123
	v_cvt_pk_bf16_f32 v107, v107, v107
	v_lshlrev_b32_e32 v108, 16, v108
	v_lshlrev_b32_e32 v124, 16, v124
	v_fmac_f32_e32 v108, v72, v124
	v_cvt_pk_bf16_f32 v108, v108, v108
	v_lshlrev_b32_e32 v109, 16, v109
	v_lshlrev_b32_e32 v125, 16, v125
	v_fmac_f32_e32 v109, v73, v125
	v_cvt_pk_bf16_f32 v109, v109, v109
	v_lshlrev_b32_e32 v110, 16, v110
	v_lshlrev_b32_e32 v126, 16, v126
	v_fmac_f32_e32 v110, v74, v126
	v_cvt_pk_bf16_f32 v110, v110, v110
	v_lshlrev_b32_e32 v111, 16, v111
	v_lshlrev_b32_e32 v127, 16, v127
	v_fmac_f32_e32 v111, v75, v127
	v_cvt_pk_bf16_f32 v111, v111, v111
	v_lshlrev_b32_e32 v112, 16, v112
	v_lshlrev_b32_e32 v128, 16, v128
	v_fmac_f32_e32 v112, v76, v128
	v_cvt_pk_bf16_f32 v112, v112, v112
	v_lshlrev_b32_e32 v113, 16, v113
	v_lshlrev_b32_e32 v129, 16, v129
	v_fmac_f32_e32 v113, v77, v129
	v_cvt_pk_bf16_f32 v113, v113, v113
	v_lshlrev_b32_e32 v114, 16, v114
	v_lshlrev_b32_e32 v130, 16, v130
	v_fmac_f32_e32 v114, v78, v130
	v_cvt_pk_bf16_f32 v114, v114, v114
	v_lshlrev_b32_e32 v115, 16, v115
	v_lshlrev_b32_e32 v131, 16, v131
	v_fmac_f32_e32 v115, v79, v131
	v_cvt_pk_bf16_f32 v115, v115, v115
	s_mov_b64 s[52:53], s[0:1]
	global_store_short v99, v100, s[52:53] offset:64
	s_add_u32 s52, s52, 0x800
	s_addc_u32 s53, s53, 0
	global_store_short v99, v101, s[52:53] offset:64
	s_add_u32 s52, s52, 0x800
	s_addc_u32 s53, s53, 0
	global_store_short v99, v102, s[52:53] offset:64
	s_add_u32 s52, s52, 0x800
	s_addc_u32 s53, s53, 0
	global_store_short v99, v103, s[52:53] offset:64
	s_add_u32 s52, s52, 0x2800
	s_addc_u32 s53, s53, 0
	global_store_short v99, v104, s[52:53] offset:64
	s_add_u32 s52, s52, 0x800
	s_addc_u32 s53, s53, 0
	global_store_short v99, v105, s[52:53] offset:64
	s_add_u32 s52, s52, 0x800
	s_addc_u32 s53, s53, 0
	global_store_short v99, v106, s[52:53] offset:64
	s_add_u32 s52, s52, 0x800
	s_addc_u32 s53, s53, 0
	global_store_short v99, v107, s[52:53] offset:64
	s_add_u32 s52, s52, 0x2800
	s_addc_u32 s53, s53, 0
	global_store_short v99, v108, s[52:53] offset:64
	s_add_u32 s52, s52, 0x800
	s_addc_u32 s53, s53, 0
	global_store_short v99, v109, s[52:53] offset:64
	s_add_u32 s52, s52, 0x800
	s_addc_u32 s53, s53, 0
	global_store_short v99, v110, s[52:53] offset:64
	s_add_u32 s52, s52, 0x800
	s_addc_u32 s53, s53, 0
	global_store_short v99, v111, s[52:53] offset:64
	s_add_u32 s52, s52, 0x2800
	s_addc_u32 s53, s53, 0
	global_store_short v99, v112, s[52:53] offset:64
	s_add_u32 s52, s52, 0x800
	s_addc_u32 s53, s53, 0
	global_store_short v99, v113, s[52:53] offset:64
	s_add_u32 s52, s52, 0x800
	s_addc_u32 s53, s53, 0
	global_store_short v99, v114, s[52:53] offset:64
	s_add_u32 s52, s52, 0x800
	s_addc_u32 s53, s53, 0
	global_store_short v99, v115, s[52:53] offset:64
	s_mov_b64 s[12:13], s[0:1]
	s_add_u32 s12, s12, 0x10000
	s_addc_u32 s13, s13, 0
	global_load_ushort v100, v99, s[12:13] offset:64
	s_add_u32 s12, s12, 0x800
	s_addc_u32 s13, s13, 0
	global_load_ushort v101, v99, s[12:13] offset:64
	s_add_u32 s12, s12, 0x800
	s_addc_u32 s13, s13, 0
	global_load_ushort v102, v99, s[12:13] offset:64
	s_add_u32 s12, s12, 0x800
	s_addc_u32 s13, s13, 0
	global_load_ushort v103, v99, s[12:13] offset:64
	s_add_u32 s12, s12, 0x2800
	s_addc_u32 s13, s13, 0
	global_load_ushort v104, v99, s[12:13] offset:64
	s_add_u32 s12, s12, 0x800
	s_addc_u32 s13, s13, 0
	global_load_ushort v105, v99, s[12:13] offset:64
	s_add_u32 s12, s12, 0x800
	s_addc_u32 s13, s13, 0
	global_load_ushort v106, v99, s[12:13] offset:64
	s_add_u32 s12, s12, 0x800
	s_addc_u32 s13, s13, 0
	global_load_ushort v107, v99, s[12:13] offset:64
	s_add_u32 s12, s12, 0x2800
	s_addc_u32 s13, s13, 0
	global_load_ushort v108, v99, s[12:13] offset:64
	s_add_u32 s12, s12, 0x800
	s_addc_u32 s13, s13, 0
	global_load_ushort v109, v99, s[12:13] offset:64
	s_add_u32 s12, s12, 0x800
	s_addc_u32 s13, s13, 0
	global_load_ushort v110, v99, s[12:13] offset:64
	s_add_u32 s12, s12, 0x800
	s_addc_u32 s13, s13, 0
	global_load_ushort v111, v99, s[12:13] offset:64
	s_add_u32 s12, s12, 0x2800
	s_addc_u32 s13, s13, 0
	global_load_ushort v112, v99, s[12:13] offset:64
	s_add_u32 s12, s12, 0x800
	s_addc_u32 s13, s13, 0
	global_load_ushort v113, v99, s[12:13] offset:64
	s_add_u32 s12, s12, 0x800
	s_addc_u32 s13, s13, 0
	global_load_ushort v114, v99, s[12:13] offset:64
	s_add_u32 s12, s12, 0x800
	s_addc_u32 s13, s13, 0
	global_load_ushort v115, v99, s[12:13] offset:64
	s_mov_b64 s[50:51], s[4:5]
	s_add_u32 s50, s50, 0x10000
	s_addc_u32 s51, s51, 0
	global_load_ushort v116, v99, s[50:51] offset:64
	s_add_u32 s50, s50, 0x800
	s_addc_u32 s51, s51, 0
	global_load_ushort v117, v99, s[50:51] offset:64
	s_add_u32 s50, s50, 0x800
	s_addc_u32 s51, s51, 0
	global_load_ushort v118, v99, s[50:51] offset:64
	s_add_u32 s50, s50, 0x800
	s_addc_u32 s51, s51, 0
	global_load_ushort v119, v99, s[50:51] offset:64
	s_add_u32 s50, s50, 0x2800
	s_addc_u32 s51, s51, 0
	global_load_ushort v120, v99, s[50:51] offset:64
	s_add_u32 s50, s50, 0x800
	s_addc_u32 s51, s51, 0
	global_load_ushort v121, v99, s[50:51] offset:64
	s_add_u32 s50, s50, 0x800
	s_addc_u32 s51, s51, 0
	global_load_ushort v122, v99, s[50:51] offset:64
	s_add_u32 s50, s50, 0x800
	s_addc_u32 s51, s51, 0
	global_load_ushort v123, v99, s[50:51] offset:64
	s_add_u32 s50, s50, 0x2800
	s_addc_u32 s51, s51, 0
	global_load_ushort v124, v99, s[50:51] offset:64
	s_add_u32 s50, s50, 0x800
	s_addc_u32 s51, s51, 0
	global_load_ushort v125, v99, s[50:51] offset:64
	s_add_u32 s50, s50, 0x800
	s_addc_u32 s51, s51, 0
	global_load_ushort v126, v99, s[50:51] offset:64
	s_add_u32 s50, s50, 0x800
	s_addc_u32 s51, s51, 0
	global_load_ushort v127, v99, s[50:51] offset:64
	s_add_u32 s50, s50, 0x2800
	s_addc_u32 s51, s51, 0
	global_load_ushort v128, v99, s[50:51] offset:64
	s_add_u32 s50, s50, 0x800
	s_addc_u32 s51, s51, 0
	global_load_ushort v129, v99, s[50:51] offset:64
	s_add_u32 s50, s50, 0x800
	s_addc_u32 s51, s51, 0
	global_load_ushort v130, v99, s[50:51] offset:64
	s_add_u32 s50, s50, 0x800
	s_addc_u32 s51, s51, 0
	global_load_ushort v131, v99, s[50:51] offset:64
	s_waitcnt vmcnt(0)
	v_lshlrev_b32_e32 v100, 16, v100
	v_lshlrev_b32_e32 v116, 16, v116
	v_fmac_f32_e32 v100, v32, v116
	v_cvt_pk_bf16_f32 v100, v100, v100
	v_lshlrev_b32_e32 v101, 16, v101
	v_lshlrev_b32_e32 v117, 16, v117
	v_fmac_f32_e32 v101, v33, v117
	v_cvt_pk_bf16_f32 v101, v101, v101
	v_lshlrev_b32_e32 v102, 16, v102
	v_lshlrev_b32_e32 v118, 16, v118
	v_fmac_f32_e32 v102, v34, v118
	v_cvt_pk_bf16_f32 v102, v102, v102
	v_lshlrev_b32_e32 v103, 16, v103
	v_lshlrev_b32_e32 v119, 16, v119
	v_fmac_f32_e32 v103, v35, v119
	v_cvt_pk_bf16_f32 v103, v103, v103
	v_lshlrev_b32_e32 v104, 16, v104
	v_lshlrev_b32_e32 v120, 16, v120
	v_fmac_f32_e32 v104, v36, v120
	v_cvt_pk_bf16_f32 v104, v104, v104
	v_lshlrev_b32_e32 v105, 16, v105
	v_lshlrev_b32_e32 v121, 16, v121
	v_fmac_f32_e32 v105, v37, v121
	v_cvt_pk_bf16_f32 v105, v105, v105
	v_lshlrev_b32_e32 v106, 16, v106
	v_lshlrev_b32_e32 v122, 16, v122
	v_fmac_f32_e32 v106, v38, v122
	v_cvt_pk_bf16_f32 v106, v106, v106
	v_lshlrev_b32_e32 v107, 16, v107
	v_lshlrev_b32_e32 v123, 16, v123
	v_fmac_f32_e32 v107, v39, v123
	v_cvt_pk_bf16_f32 v107, v107, v107
	v_lshlrev_b32_e32 v108, 16, v108
	v_lshlrev_b32_e32 v124, 16, v124
	v_fmac_f32_e32 v108, v40, v124
	v_cvt_pk_bf16_f32 v108, v108, v108
	v_lshlrev_b32_e32 v109, 16, v109
	v_lshlrev_b32_e32 v125, 16, v125
	v_fmac_f32_e32 v109, v41, v125
	v_cvt_pk_bf16_f32 v109, v109, v109
	v_lshlrev_b32_e32 v110, 16, v110
	v_lshlrev_b32_e32 v126, 16, v126
	v_fmac_f32_e32 v110, v42, v126
	v_cvt_pk_bf16_f32 v110, v110, v110
	v_lshlrev_b32_e32 v111, 16, v111
	v_lshlrev_b32_e32 v127, 16, v127
	v_fmac_f32_e32 v111, v43, v127
	v_cvt_pk_bf16_f32 v111, v111, v111
	v_lshlrev_b32_e32 v112, 16, v112
	v_lshlrev_b32_e32 v128, 16, v128
	v_fmac_f32_e32 v112, v44, v128
	v_cvt_pk_bf16_f32 v112, v112, v112
	v_lshlrev_b32_e32 v113, 16, v113
	v_lshlrev_b32_e32 v129, 16, v129
	v_fmac_f32_e32 v113, v45, v129
	v_cvt_pk_bf16_f32 v113, v113, v113
	v_lshlrev_b32_e32 v114, 16, v114
	v_lshlrev_b32_e32 v130, 16, v130
	v_fmac_f32_e32 v114, v46, v130
	v_cvt_pk_bf16_f32 v114, v114, v114
	v_lshlrev_b32_e32 v115, 16, v115
	v_lshlrev_b32_e32 v131, 16, v131
	v_fmac_f32_e32 v115, v47, v131
	v_cvt_pk_bf16_f32 v115, v115, v115
	s_mov_b64 s[52:53], s[0:1]
	s_add_u32 s52, s52, 0x10000
	s_addc_u32 s53, s53, 0
	global_store_short v99, v100, s[52:53] offset:64
	s_add_u32 s52, s52, 0x800
	s_addc_u32 s53, s53, 0
	global_store_short v99, v101, s[52:53] offset:64
	s_add_u32 s52, s52, 0x800
	s_addc_u32 s53, s53, 0
	global_store_short v99, v102, s[52:53] offset:64
	s_add_u32 s52, s52, 0x800
	s_addc_u32 s53, s53, 0
	global_store_short v99, v103, s[52:53] offset:64
	s_add_u32 s52, s52, 0x2800
	s_addc_u32 s53, s53, 0
	global_store_short v99, v104, s[52:53] offset:64
	s_add_u32 s52, s52, 0x800
	s_addc_u32 s53, s53, 0
	global_store_short v99, v105, s[52:53] offset:64
	s_add_u32 s52, s52, 0x800
	s_addc_u32 s53, s53, 0
	global_store_short v99, v106, s[52:53] offset:64
	s_add_u32 s52, s52, 0x800
	s_addc_u32 s53, s53, 0
	global_store_short v99, v107, s[52:53] offset:64
	s_add_u32 s52, s52, 0x2800
	s_addc_u32 s53, s53, 0
	global_store_short v99, v108, s[52:53] offset:64
	s_add_u32 s52, s52, 0x800
	s_addc_u32 s53, s53, 0
	global_store_short v99, v109, s[52:53] offset:64
	s_add_u32 s52, s52, 0x800
	s_addc_u32 s53, s53, 0
	global_store_short v99, v110, s[52:53] offset:64
	s_add_u32 s52, s52, 0x800
	s_addc_u32 s53, s53, 0
	global_store_short v99, v111, s[52:53] offset:64
	s_add_u32 s52, s52, 0x2800
	s_addc_u32 s53, s53, 0
	global_store_short v99, v112, s[52:53] offset:64
	s_add_u32 s52, s52, 0x800
	s_addc_u32 s53, s53, 0
	global_store_short v99, v113, s[52:53] offset:64
	s_add_u32 s52, s52, 0x800
	s_addc_u32 s53, s53, 0
	global_store_short v99, v114, s[52:53] offset:64
	s_add_u32 s52, s52, 0x800
	s_addc_u32 s53, s53, 0
	global_store_short v99, v115, s[52:53] offset:64
	s_mov_b64 s[12:13], s[0:1]
	s_add_u32 s12, s12, 0x20000
	s_addc_u32 s13, s13, 0
	global_load_ushort v100, v99, s[12:13] offset:64
	s_add_u32 s12, s12, 0x800
	s_addc_u32 s13, s13, 0
	global_load_ushort v101, v99, s[12:13] offset:64
	s_add_u32 s12, s12, 0x800
	s_addc_u32 s13, s13, 0
	global_load_ushort v102, v99, s[12:13] offset:64
	s_add_u32 s12, s12, 0x800
	s_addc_u32 s13, s13, 0
	global_load_ushort v103, v99, s[12:13] offset:64
	s_add_u32 s12, s12, 0x2800
	s_addc_u32 s13, s13, 0
	global_load_ushort v104, v99, s[12:13] offset:64
	s_add_u32 s12, s12, 0x800
	s_addc_u32 s13, s13, 0
	global_load_ushort v105, v99, s[12:13] offset:64
	s_add_u32 s12, s12, 0x800
	s_addc_u32 s13, s13, 0
	global_load_ushort v106, v99, s[12:13] offset:64
	s_add_u32 s12, s12, 0x800
	s_addc_u32 s13, s13, 0
	global_load_ushort v107, v99, s[12:13] offset:64
	s_add_u32 s12, s12, 0x2800
	s_addc_u32 s13, s13, 0
	global_load_ushort v108, v99, s[12:13] offset:64
	s_add_u32 s12, s12, 0x800
	s_addc_u32 s13, s13, 0
	global_load_ushort v109, v99, s[12:13] offset:64
	s_add_u32 s12, s12, 0x800
	s_addc_u32 s13, s13, 0
	global_load_ushort v110, v99, s[12:13] offset:64
	s_add_u32 s12, s12, 0x800
	s_addc_u32 s13, s13, 0
	global_load_ushort v111, v99, s[12:13] offset:64
	s_add_u32 s12, s12, 0x2800
	s_addc_u32 s13, s13, 0
	global_load_ushort v112, v99, s[12:13] offset:64
	s_add_u32 s12, s12, 0x800
	s_addc_u32 s13, s13, 0
	global_load_ushort v113, v99, s[12:13] offset:64
	s_add_u32 s12, s12, 0x800
	s_addc_u32 s13, s13, 0
	global_load_ushort v114, v99, s[12:13] offset:64
	s_add_u32 s12, s12, 0x800
	s_addc_u32 s13, s13, 0
	global_load_ushort v115, v99, s[12:13] offset:64
	s_mov_b64 s[50:51], s[4:5]
	s_add_u32 s50, s50, 0x20000
	s_addc_u32 s51, s51, 0
	global_load_ushort v116, v99, s[50:51] offset:64
	s_add_u32 s50, s50, 0x800
	s_addc_u32 s51, s51, 0
	global_load_ushort v117, v99, s[50:51] offset:64
	s_add_u32 s50, s50, 0x800
	s_addc_u32 s51, s51, 0
	global_load_ushort v118, v99, s[50:51] offset:64
	s_add_u32 s50, s50, 0x800
	s_addc_u32 s51, s51, 0
	global_load_ushort v119, v99, s[50:51] offset:64
	s_add_u32 s50, s50, 0x2800
	s_addc_u32 s51, s51, 0
	global_load_ushort v120, v99, s[50:51] offset:64
	s_add_u32 s50, s50, 0x800
	s_addc_u32 s51, s51, 0
	global_load_ushort v121, v99, s[50:51] offset:64
	s_add_u32 s50, s50, 0x800
	s_addc_u32 s51, s51, 0
	global_load_ushort v122, v99, s[50:51] offset:64
	s_add_u32 s50, s50, 0x800
	s_addc_u32 s51, s51, 0
	global_load_ushort v123, v99, s[50:51] offset:64
	s_add_u32 s50, s50, 0x2800
	s_addc_u32 s51, s51, 0
	global_load_ushort v124, v99, s[50:51] offset:64
	s_add_u32 s50, s50, 0x800
	s_addc_u32 s51, s51, 0
	global_load_ushort v125, v99, s[50:51] offset:64
	s_add_u32 s50, s50, 0x800
	s_addc_u32 s51, s51, 0
	global_load_ushort v126, v99, s[50:51] offset:64
	s_add_u32 s50, s50, 0x800
	s_addc_u32 s51, s51, 0
	global_load_ushort v127, v99, s[50:51] offset:64
	s_add_u32 s50, s50, 0x2800
	s_addc_u32 s51, s51, 0
	global_load_ushort v128, v99, s[50:51] offset:64
	s_add_u32 s50, s50, 0x800
	s_addc_u32 s51, s51, 0
	global_load_ushort v129, v99, s[50:51] offset:64
	s_add_u32 s50, s50, 0x800
	s_addc_u32 s51, s51, 0
	global_load_ushort v130, v99, s[50:51] offset:64
	s_add_u32 s50, s50, 0x800
	s_addc_u32 s51, s51, 0
	global_load_ushort v131, v99, s[50:51] offset:64
	s_waitcnt vmcnt(0)
	v_lshlrev_b32_e32 v100, 16, v100
	v_lshlrev_b32_e32 v116, 16, v116
	v_fmac_f32_e32 v100, v0, v116
	v_cvt_pk_bf16_f32 v100, v100, v100
	v_lshlrev_b32_e32 v101, 16, v101
	v_lshlrev_b32_e32 v117, 16, v117
	v_fmac_f32_e32 v101, v1, v117
	v_cvt_pk_bf16_f32 v101, v101, v101
	v_lshlrev_b32_e32 v102, 16, v102
	v_lshlrev_b32_e32 v118, 16, v118
	v_fmac_f32_e32 v102, v2, v118
	v_cvt_pk_bf16_f32 v102, v102, v102
	v_lshlrev_b32_e32 v103, 16, v103
	v_lshlrev_b32_e32 v119, 16, v119
	v_fmac_f32_e32 v103, v3, v119
	v_cvt_pk_bf16_f32 v103, v103, v103
	v_lshlrev_b32_e32 v104, 16, v104
	v_lshlrev_b32_e32 v120, 16, v120
	v_fmac_f32_e32 v104, v4, v120
	v_cvt_pk_bf16_f32 v104, v104, v104
	v_lshlrev_b32_e32 v105, 16, v105
	v_lshlrev_b32_e32 v121, 16, v121
	v_fmac_f32_e32 v105, v5, v121
	v_cvt_pk_bf16_f32 v105, v105, v105
	v_lshlrev_b32_e32 v106, 16, v106
	v_lshlrev_b32_e32 v122, 16, v122
	v_fmac_f32_e32 v106, v6, v122
	v_cvt_pk_bf16_f32 v106, v106, v106
	v_lshlrev_b32_e32 v107, 16, v107
	v_lshlrev_b32_e32 v123, 16, v123
	v_fmac_f32_e32 v107, v7, v123
	v_cvt_pk_bf16_f32 v107, v107, v107
	v_lshlrev_b32_e32 v108, 16, v108
	v_lshlrev_b32_e32 v124, 16, v124
	v_fmac_f32_e32 v108, v8, v124
	v_cvt_pk_bf16_f32 v108, v108, v108
	v_lshlrev_b32_e32 v109, 16, v109
	v_lshlrev_b32_e32 v125, 16, v125
	v_fmac_f32_e32 v109, v9, v125
	v_cvt_pk_bf16_f32 v109, v109, v109
	v_lshlrev_b32_e32 v110, 16, v110
	v_lshlrev_b32_e32 v126, 16, v126
	v_fmac_f32_e32 v110, v10, v126
	v_cvt_pk_bf16_f32 v110, v110, v110
	v_lshlrev_b32_e32 v111, 16, v111
	v_lshlrev_b32_e32 v127, 16, v127
	v_fmac_f32_e32 v111, v11, v127
	v_cvt_pk_bf16_f32 v111, v111, v111
	v_lshlrev_b32_e32 v112, 16, v112
	v_lshlrev_b32_e32 v128, 16, v128
	v_fmac_f32_e32 v112, v12, v128
	v_cvt_pk_bf16_f32 v112, v112, v112
	v_lshlrev_b32_e32 v113, 16, v113
	v_lshlrev_b32_e32 v129, 16, v129
	v_fmac_f32_e32 v113, v13, v129
	v_cvt_pk_bf16_f32 v113, v113, v113
	v_lshlrev_b32_e32 v114, 16, v114
	v_lshlrev_b32_e32 v130, 16, v130
	v_fmac_f32_e32 v114, v14, v130
	v_cvt_pk_bf16_f32 v114, v114, v114
	v_lshlrev_b32_e32 v115, 16, v115
	v_lshlrev_b32_e32 v131, 16, v131
	v_fmac_f32_e32 v115, v15, v131
	v_cvt_pk_bf16_f32 v115, v115, v115
	s_mov_b64 s[52:53], s[0:1]
	s_add_u32 s52, s52, 0x20000
	s_addc_u32 s53, s53, 0
	global_store_short v99, v100, s[52:53] offset:64
	s_add_u32 s52, s52, 0x800
	s_addc_u32 s53, s53, 0
	global_store_short v99, v101, s[52:53] offset:64
	s_add_u32 s52, s52, 0x800
	s_addc_u32 s53, s53, 0
	global_store_short v99, v102, s[52:53] offset:64
	s_add_u32 s52, s52, 0x800
	s_addc_u32 s53, s53, 0
	global_store_short v99, v103, s[52:53] offset:64
	s_add_u32 s52, s52, 0x2800
	s_addc_u32 s53, s53, 0
	global_store_short v99, v104, s[52:53] offset:64
	s_add_u32 s52, s52, 0x800
	s_addc_u32 s53, s53, 0
	global_store_short v99, v105, s[52:53] offset:64
	s_add_u32 s52, s52, 0x800
	s_addc_u32 s53, s53, 0
	global_store_short v99, v106, s[52:53] offset:64
	s_add_u32 s52, s52, 0x800
	s_addc_u32 s53, s53, 0
	global_store_short v99, v107, s[52:53] offset:64
	s_add_u32 s52, s52, 0x2800
	s_addc_u32 s53, s53, 0
	global_store_short v99, v108, s[52:53] offset:64
	s_add_u32 s52, s52, 0x800
	s_addc_u32 s53, s53, 0
	global_store_short v99, v109, s[52:53] offset:64
	s_add_u32 s52, s52, 0x800
	s_addc_u32 s53, s53, 0
	global_store_short v99, v110, s[52:53] offset:64
	s_add_u32 s52, s52, 0x800
	s_addc_u32 s53, s53, 0
	global_store_short v99, v111, s[52:53] offset:64
	s_add_u32 s52, s52, 0x2800
	s_addc_u32 s53, s53, 0
	global_store_short v99, v112, s[52:53] offset:64
	s_add_u32 s52, s52, 0x800
	s_addc_u32 s53, s53, 0
	global_store_short v99, v113, s[52:53] offset:64
	s_add_u32 s52, s52, 0x800
	s_addc_u32 s53, s53, 0
	global_store_short v99, v114, s[52:53] offset:64
	s_add_u32 s52, s52, 0x800
	s_addc_u32 s53, s53, 0
	global_store_short v99, v115, s[52:53] offset:64
	s_mov_b64 s[50:51], 0x50000
	s_mov_b64 s[52:53], 0x50180
	s_load_dword s0, s[90:91], 0x0
	s_waitcnt lgkmcnt(0)
	s_add_i32 s14, s14, s0
	s_cmpk_lt_i32 s14, 0x200
	s_cbranch_scc1 .LBB0_777
